# A/B: hipcc's 96 per-block s_setprio flips in the GEMM K-loops deleted
# speedup vs baseline: 1.0172x; 1.0060x over previous
.LBB0_218:
	ds_read_b128 v[152:155], v149
	ds_read_b128 v[156:159], v149 offset:1024
	ds_read_b128 v[160:163], v149 offset:2048
	ds_read_b128 v[164:167], v149 offset:3072
	ds_read_b128 v[168:171], v150
	ds_read_b128 v[172:175], v150 offset:1024
	ds_read_b128 v[176:179], v150 offset:2048
	ds_read_b128 v[180:183], v150 offset:3072
	s_add_u32 s45, s42, 0xfffc0080
	s_addc_u32 s48, s43, -1
	s_cmp_eq_u32 s44, 12
	s_cselect_b32 s57, s39, s48
	s_cselect_b32 s56, s38, s45
	s_cselect_b32 s49, s41, s31
	s_cselect_b32 s48, s40, s27
	v_lshl_add_u64 v[216:217], s[42:43], 0, v[138:139]
	s_add_i32 m0, s29, 0xc000
	ds_read_b128 v[184:187], v151
	ds_read_b128 v[188:191], v151 offset:1024
	ds_read_b128 v[192:195], v151 offset:2048
	ds_read_b128 v[196:199], v151 offset:3072
	ds_read_b128 v[200:203], v151 offset:4096
	ds_read_b128 v[204:207], v151 offset:5120
	ds_read_b128 v[208:211], v151 offset:6144
	ds_read_b128 v[212:215], v151 offset:7168
	global_load_lds_dwordx4 v[216:217], off
	v_lshl_add_u64 v[216:217], s[42:43], 0, v[140:141]
	s_add_i32 m0, s29, 0xe000
	s_nop 0
	global_load_lds_dwordx4 v[216:217], off
	s_waitcnt vmcnt(8)
	s_waitcnt lgkmcnt(0)
	s_barrier
	s_waitcnt lgkmcnt(0)
	v_mfma_f32_16x16x32_bf16 v[126:129], v[152:155], v[184:187], v[126:129]
	v_mfma_f32_16x16x32_bf16 v[122:125], v[160:163], v[184:187], v[122:125]
	v_mfma_f32_16x16x32_bf16 v[118:121], v[152:155], v[192:195], v[118:121]
	v_mfma_f32_16x16x32_bf16 v[114:117], v[160:163], v[192:195], v[114:117]
	v_mfma_f32_16x16x32_bf16 v[102:105], v[152:155], v[200:203], v[102:105]
	v_mfma_f32_16x16x32_bf16 v[98:101], v[160:163], v[200:203], v[98:101]
	v_mfma_f32_16x16x32_bf16 v[86:89], v[152:155], v[208:211], v[86:89]
	v_mfma_f32_16x16x32_bf16 v[82:85], v[160:163], v[208:211], v[82:85]
	v_mfma_f32_16x16x32_bf16 v[126:129], v[156:159], v[188:191], v[126:129]
	v_mfma_f32_16x16x32_bf16 v[122:125], v[164:167], v[188:191], v[122:125]
	v_mfma_f32_16x16x32_bf16 v[118:121], v[156:159], v[196:199], v[118:121]
	v_mfma_f32_16x16x32_bf16 v[114:117], v[164:167], v[196:199], v[114:117]
	v_mfma_f32_16x16x32_bf16 v[102:105], v[156:159], v[204:207], v[102:105]
	v_mfma_f32_16x16x32_bf16 v[98:101], v[164:167], v[204:207], v[98:101]
	v_mfma_f32_16x16x32_bf16 v[86:89], v[156:159], v[212:215], v[86:89]
	v_mfma_f32_16x16x32_bf16 v[82:85], v[164:167], v[212:215], v[82:85]
	v_mfma_f32_16x16x32_bf16 v[110:113], v[168:171], v[184:187], v[110:113]
	v_mfma_f32_16x16x32_bf16 v[106:109], v[176:179], v[184:187], v[106:109]
	v_mfma_f32_16x16x32_bf16 v[94:97], v[168:171], v[192:195], v[94:97]
	v_mfma_f32_16x16x32_bf16 v[90:93], v[176:179], v[192:195], v[90:93]
	v_mfma_f32_16x16x32_bf16 v[78:81], v[168:171], v[200:203], v[78:81]
	v_mfma_f32_16x16x32_bf16 v[74:77], v[176:179], v[200:203], v[74:77]
	v_mfma_f32_16x16x32_bf16 v[70:73], v[168:171], v[208:211], v[70:73]
	v_mfma_f32_16x16x32_bf16 v[66:69], v[176:179], v[208:211], v[66:69]
	v_mfma_f32_16x16x32_bf16 v[110:113], v[172:175], v[188:191], v[110:113]
	v_mfma_f32_16x16x32_bf16 v[106:109], v[180:183], v[188:191], v[106:109]
	v_mfma_f32_16x16x32_bf16 v[94:97], v[172:175], v[196:199], v[94:97]
	v_mfma_f32_16x16x32_bf16 v[90:93], v[180:183], v[196:199], v[90:93]
	v_mfma_f32_16x16x32_bf16 v[78:81], v[172:175], v[204:207], v[78:81]
	v_mfma_f32_16x16x32_bf16 v[74:77], v[180:183], v[204:207], v[74:77]
	v_mfma_f32_16x16x32_bf16 v[70:73], v[172:175], v[212:215], v[70:73]
	v_mfma_f32_16x16x32_bf16 v[66:69], v[180:183], v[212:215], v[66:69]
	s_barrier
	s_add_i32 s45, s80, s59
	v_lshl_add_u64 v[216:217], s[48:49], 0, v[132:133]
	s_mov_b32 m0, s45
	ds_read_b128 v[184:187], v151 offset:16384
	ds_read_b128 v[188:191], v151 offset:17408
	ds_read_b128 v[192:195], v151 offset:18432
	ds_read_b128 v[196:199], v151 offset:19456
	ds_read_b128 v[200:203], v151 offset:20480
	ds_read_b128 v[204:207], v151 offset:21504
	ds_read_b128 v[208:211], v151 offset:22528
	ds_read_b128 v[212:215], v151 offset:23552
	global_load_lds_dwordx4 v[216:217], off
	s_add_i32 m0, s45, 0x2000
	s_add_u32 s92, s48, 0x40000
	v_lshl_add_u64 v[218:219], s[48:49], 0, v[136:137]
	s_addc_u32 s93, s49, 0
	s_add_i32 s45, s81, s59
	global_load_lds_dwordx4 v[218:219], off
	v_lshl_add_u64 v[220:221], s[92:93], 0, v[132:133]
	s_mov_b32 m0, s45
	v_lshl_add_u64 v[222:223], s[56:57], 0, v[134:135]
	global_load_lds_dwordx4 v[220:221], off
	v_lshl_add_u64 v[220:221], s[92:93], 0, v[136:137]
	s_add_i32 m0, s45, 0x2000
	s_nop 0
	global_load_lds_dwordx4 v[220:221], off
	v_lshl_add_u64 v[220:221], s[56:57], 0, v[130:131]
	s_mov_b32 m0, s29
	s_nop 0
	global_load_lds_dwordx4 v[220:221], off
	s_mov_b32 m0, s62
	s_nop 0
	global_load_lds_dwordx4 v[222:223], off
	s_waitcnt vmcnt(8)
	s_waitcnt lgkmcnt(0)
	s_barrier
	s_waitcnt lgkmcnt(0)
	v_mfma_f32_16x16x32_bf16 v[62:65], v[152:155], v[184:187], v[62:65]
	v_mfma_f32_16x16x32_bf16 v[58:61], v[160:163], v[184:187], v[58:61]
	v_mfma_f32_16x16x32_bf16 v[54:57], v[152:155], v[192:195], v[54:57]
	v_mfma_f32_16x16x32_bf16 v[50:53], v[160:163], v[192:195], v[50:53]
	v_mfma_f32_16x16x32_bf16 v[38:41], v[152:155], v[200:203], v[38:41]
	v_mfma_f32_16x16x32_bf16 v[34:37], v[160:163], v[200:203], v[34:37]
	v_mfma_f32_16x16x32_bf16 v[22:25], v[152:155], v[208:211], v[22:25]
	v_mfma_f32_16x16x32_bf16 v[18:21], v[160:163], v[208:211], v[18:21]
	v_mfma_f32_16x16x32_bf16 v[62:65], v[156:159], v[188:191], v[62:65]
	v_mfma_f32_16x16x32_bf16 v[58:61], v[164:167], v[188:191], v[58:61]
	v_mfma_f32_16x16x32_bf16 v[54:57], v[156:159], v[196:199], v[54:57]
	v_mfma_f32_16x16x32_bf16 v[50:53], v[164:167], v[196:199], v[50:53]
	v_mfma_f32_16x16x32_bf16 v[38:41], v[156:159], v[204:207], v[38:41]
	v_mfma_f32_16x16x32_bf16 v[34:37], v[164:167], v[204:207], v[34:37]
	v_mfma_f32_16x16x32_bf16 v[22:25], v[156:159], v[212:215], v[22:25]
	v_mfma_f32_16x16x32_bf16 v[18:21], v[164:167], v[212:215], v[18:21]
	v_mfma_f32_16x16x32_bf16 v[46:49], v[168:171], v[184:187], v[46:49]
	v_mfma_f32_16x16x32_bf16 v[42:45], v[176:179], v[184:187], v[42:45]
	v_mfma_f32_16x16x32_bf16 v[30:33], v[168:171], v[192:195], v[30:33]
	v_mfma_f32_16x16x32_bf16 v[26:29], v[176:179], v[192:195], v[26:29]
	v_mfma_f32_16x16x32_bf16 v[14:17], v[168:171], v[200:203], v[14:17]
	v_mfma_f32_16x16x32_bf16 v[10:13], v[176:179], v[200:203], v[10:13]
	v_mfma_f32_16x16x32_bf16 v[6:9], v[168:171], v[208:211], v[6:9]
	v_mfma_f32_16x16x32_bf16 v[2:5], v[176:179], v[208:211], v[2:5]
	v_mfma_f32_16x16x32_bf16 v[46:49], v[172:175], v[188:191], v[46:49]
	v_mfma_f32_16x16x32_bf16 v[42:45], v[180:183], v[188:191], v[42:45]
	v_mfma_f32_16x16x32_bf16 v[30:33], v[172:175], v[196:199], v[30:33]
	v_mfma_f32_16x16x32_bf16 v[26:29], v[180:183], v[196:199], v[26:29]
	v_mfma_f32_16x16x32_bf16 v[14:17], v[172:175], v[204:207], v[14:17]
	v_mfma_f32_16x16x32_bf16 v[10:13], v[180:183], v[204:207], v[10:13]
	v_mfma_f32_16x16x32_bf16 v[6:9], v[172:175], v[212:215], v[6:9]
	v_mfma_f32_16x16x32_bf16 v[2:5], v[180:183], v[212:215], v[2:5]
	s_barrier
	s_add_i32 s45, 0, 0x18000
	s_add_i32 s91, 0, 0x1c000
	v_add_u32_e32 v164, s45, v147
	v_add_u32_e32 v180, s91, v147
	ds_read_b128 v[152:155], v164
	ds_read_b128 v[156:159], v164 offset:1024
	ds_read_b128 v[160:163], v164 offset:2048
	ds_read_b128 v[164:167], v164 offset:3072
	ds_read_b128 v[168:171], v180
	ds_read_b128 v[172:175], v180 offset:1024
	ds_read_b128 v[176:179], v180 offset:2048
	ds_read_b128 v[180:183], v180 offset:3072
	s_add_u32 s56, s56, 0x40000
	s_addc_u32 s57, s57, 0
	s_mov_b32 m0, s63
	v_lshl_add_u64 v[224:225], s[56:57], 0, v[130:131]
	ds_read_b128 v[184:187], v151 offset:32768
	ds_read_b128 v[188:191], v151 offset:33792
	ds_read_b128 v[192:195], v151 offset:34816
	ds_read_b128 v[196:199], v151 offset:35840
	ds_read_b128 v[200:203], v151 offset:36864
	ds_read_b128 v[204:207], v151 offset:37888
	ds_read_b128 v[208:211], v151 offset:38912
	ds_read_b128 v[212:215], v151 offset:39936
	global_load_lds_dwordx4 v[224:225], off
	v_lshl_add_u64 v[224:225], s[56:57], 0, v[134:135]
	s_mov_b32 m0, s74
	s_nop 0
	global_load_lds_dwordx4 v[224:225], off
	s_waitcnt vmcnt(8)
	s_waitcnt lgkmcnt(0)
	s_barrier
	s_waitcnt lgkmcnt(0)
	v_mfma_f32_16x16x32_bf16 v[126:129], v[152:155], v[184:187], v[126:129]
	v_mfma_f32_16x16x32_bf16 v[122:125], v[160:163], v[184:187], v[122:125]
	v_mfma_f32_16x16x32_bf16 v[118:121], v[152:155], v[192:195], v[118:121]
	v_mfma_f32_16x16x32_bf16 v[114:117], v[160:163], v[192:195], v[114:117]
	v_mfma_f32_16x16x32_bf16 v[102:105], v[152:155], v[200:203], v[102:105]
	v_mfma_f32_16x16x32_bf16 v[98:101], v[160:163], v[200:203], v[98:101]
	v_mfma_f32_16x16x32_bf16 v[86:89], v[152:155], v[208:211], v[86:89]
	v_mfma_f32_16x16x32_bf16 v[82:85], v[160:163], v[208:211], v[82:85]
	v_mfma_f32_16x16x32_bf16 v[126:129], v[156:159], v[188:191], v[126:129]
	v_mfma_f32_16x16x32_bf16 v[122:125], v[164:167], v[188:191], v[122:125]
	v_mfma_f32_16x16x32_bf16 v[118:121], v[156:159], v[196:199], v[118:121]
	v_mfma_f32_16x16x32_bf16 v[114:117], v[164:167], v[196:199], v[114:117]
	v_mfma_f32_16x16x32_bf16 v[102:105], v[156:159], v[204:207], v[102:105]
	v_mfma_f32_16x16x32_bf16 v[98:101], v[164:167], v[204:207], v[98:101]
	v_mfma_f32_16x16x32_bf16 v[86:89], v[156:159], v[212:215], v[86:89]
	v_mfma_f32_16x16x32_bf16 v[82:85], v[164:167], v[212:215], v[82:85]
	v_mfma_f32_16x16x32_bf16 v[110:113], v[168:171], v[184:187], v[110:113]
	v_mfma_f32_16x16x32_bf16 v[106:109], v[176:179], v[184:187], v[106:109]
	v_mfma_f32_16x16x32_bf16 v[94:97], v[168:171], v[192:195], v[94:97]
	v_mfma_f32_16x16x32_bf16 v[90:93], v[176:179], v[192:195], v[90:93]
	v_mfma_f32_16x16x32_bf16 v[78:81], v[168:171], v[200:203], v[78:81]
	v_mfma_f32_16x16x32_bf16 v[74:77], v[176:179], v[200:203], v[74:77]
	v_mfma_f32_16x16x32_bf16 v[70:73], v[168:171], v[208:211], v[70:73]
	v_mfma_f32_16x16x32_bf16 v[66:69], v[176:179], v[208:211], v[66:69]
	v_mfma_f32_16x16x32_bf16 v[110:113], v[172:175], v[188:191], v[110:113]
	v_mfma_f32_16x16x32_bf16 v[106:109], v[180:183], v[188:191], v[106:109]
	v_mfma_f32_16x16x32_bf16 v[94:97], v[172:175], v[196:199], v[94:97]
	v_mfma_f32_16x16x32_bf16 v[90:93], v[180:183], v[196:199], v[90:93]
	v_mfma_f32_16x16x32_bf16 v[78:81], v[172:175], v[204:207], v[78:81]
	v_mfma_f32_16x16x32_bf16 v[74:77], v[180:183], v[204:207], v[74:77]
	v_mfma_f32_16x16x32_bf16 v[70:73], v[172:175], v[212:215], v[70:73]
	v_mfma_f32_16x16x32_bf16 v[66:69], v[180:183], v[212:215], v[66:69]
	s_barrier
	s_add_i32 s45, s45, s59
	v_lshl_add_u64 v[216:217], v[216:217], 0, s[14:15]
	s_mov_b32 m0, s45
	ds_read_b128 v[184:187], v151 offset:49152
	ds_read_b128 v[188:191], v151 offset:50176
	ds_read_b128 v[192:195], v151 offset:51200
	ds_read_b128 v[196:199], v151 offset:52224
	ds_read_b128 v[200:203], v151 offset:53248
	ds_read_b128 v[204:207], v151 offset:54272
	ds_read_b128 v[208:211], v151 offset:55296
	ds_read_b128 v[212:215], v151 offset:56320
	global_load_lds_dwordx4 v[216:217], off
	s_add_i32 m0, s45, 0x2000
	s_add_u32 s48, s48, 0x40080
	v_lshl_add_u64 v[216:217], v[218:219], 0, s[14:15]
	s_addc_u32 s49, s49, 0
	s_add_i32 s45, s91, s59
	global_load_lds_dwordx4 v[216:217], off
	v_lshl_add_u64 v[216:217], s[48:49], 0, v[132:133]
	s_mov_b32 m0, s45
	s_nop 0
	global_load_lds_dwordx4 v[216:217], off
	v_lshl_add_u64 v[216:217], s[48:49], 0, v[136:137]
	s_add_i32 m0, s45, 0x2000
	s_nop 0
	global_load_lds_dwordx4 v[216:217], off
	v_lshl_add_u64 v[216:217], v[220:221], 0, s[14:15]
	s_mov_b32 m0, s77
	s_nop 0
	global_load_lds_dwordx4 v[216:217], off
	v_lshl_add_u64 v[216:217], v[222:223], 0, s[14:15]
	s_mov_b32 m0, s78
	s_nop 0
	global_load_lds_dwordx4 v[216:217], off
	s_waitcnt vmcnt(8)
	s_waitcnt lgkmcnt(0)
	s_barrier
	s_waitcnt lgkmcnt(0)
	v_mfma_f32_16x16x32_bf16 v[62:65], v[152:155], v[184:187], v[62:65]
	v_mfma_f32_16x16x32_bf16 v[58:61], v[160:163], v[184:187], v[58:61]
	v_mfma_f32_16x16x32_bf16 v[54:57], v[152:155], v[192:195], v[54:57]
	v_mfma_f32_16x16x32_bf16 v[50:53], v[160:163], v[192:195], v[50:53]
	v_mfma_f32_16x16x32_bf16 v[38:41], v[152:155], v[200:203], v[38:41]
	v_mfma_f32_16x16x32_bf16 v[34:37], v[160:163], v[200:203], v[34:37]
	v_mfma_f32_16x16x32_bf16 v[22:25], v[152:155], v[208:211], v[22:25]
	v_mfma_f32_16x16x32_bf16 v[18:21], v[160:163], v[208:211], v[18:21]
	v_mfma_f32_16x16x32_bf16 v[62:65], v[156:159], v[188:191], v[62:65]
	v_mfma_f32_16x16x32_bf16 v[58:61], v[164:167], v[188:191], v[58:61]
	v_mfma_f32_16x16x32_bf16 v[54:57], v[156:159], v[196:199], v[54:57]
	v_mfma_f32_16x16x32_bf16 v[50:53], v[164:167], v[196:199], v[50:53]
	v_mfma_f32_16x16x32_bf16 v[38:41], v[156:159], v[204:207], v[38:41]
	v_mfma_f32_16x16x32_bf16 v[34:37], v[164:167], v[204:207], v[34:37]
	v_mfma_f32_16x16x32_bf16 v[22:25], v[156:159], v[212:215], v[22:25]
	v_mfma_f32_16x16x32_bf16 v[18:21], v[164:167], v[212:215], v[18:21]
	v_mfma_f32_16x16x32_bf16 v[46:49], v[168:171], v[184:187], v[46:49]
	v_mfma_f32_16x16x32_bf16 v[42:45], v[176:179], v[184:187], v[42:45]
	v_mfma_f32_16x16x32_bf16 v[30:33], v[168:171], v[192:195], v[30:33]
	v_mfma_f32_16x16x32_bf16 v[26:29], v[176:179], v[192:195], v[26:29]
	v_mfma_f32_16x16x32_bf16 v[14:17], v[168:171], v[200:203], v[14:17]
	v_mfma_f32_16x16x32_bf16 v[10:13], v[176:179], v[200:203], v[10:13]
	v_mfma_f32_16x16x32_bf16 v[6:9], v[168:171], v[208:211], v[6:9]
	v_mfma_f32_16x16x32_bf16 v[2:5], v[176:179], v[208:211], v[2:5]
	v_mfma_f32_16x16x32_bf16 v[46:49], v[172:175], v[188:191], v[46:49]
	v_mfma_f32_16x16x32_bf16 v[42:45], v[180:183], v[188:191], v[42:45]
	v_mfma_f32_16x16x32_bf16 v[30:33], v[172:175], v[196:199], v[30:33]
	v_mfma_f32_16x16x32_bf16 v[26:29], v[180:183], v[196:199], v[26:29]
	v_mfma_f32_16x16x32_bf16 v[14:17], v[172:175], v[204:207], v[14:17]
	v_mfma_f32_16x16x32_bf16 v[10:13], v[180:183], v[204:207], v[10:13]
	v_mfma_f32_16x16x32_bf16 v[6:9], v[172:175], v[212:215], v[6:9]
	v_mfma_f32_16x16x32_bf16 v[2:5], v[180:183], v[212:215], v[2:5]
	s_barrier
	s_add_i32 s44, s44, 2
	s_add_u32 s42, s42, 0x100
	s_addc_u32 s43, s43, 0
	s_add_u32 s27, s27, 0x100
	s_addc_u32 s31, s31, 0
	s_cmp_gt_u32 s44, 13
	s_cbranch_scc0 .LBB0_218
	s_and_b64 vcc, exec, s[16:17]
	s_cbranch_vccz .LBB0_221
	s_barrier

.LBB0_590:
	ds_read_b128 v[130:133], v175
	ds_read_b128 v[134:137], v175 offset:1024
	ds_read_b128 v[156:159], v175 offset:2048
	ds_read_b128 v[160:163], v175 offset:3072
	ds_read_b128 v[164:167], v176
	ds_read_b128 v[168:171], v176 offset:1024
	ds_read_b128 v[180:183], v176 offset:2048
	ds_read_b128 v[184:187], v176 offset:3072
	s_add_u32 s12, s10, 0xfffc0080
	s_addc_u32 s13, s11, -1
	s_cmp_eq_u32 s45, 12
	s_cselect_b32 s63, s7, s13
	s_cselect_b32 s62, s6, s12
	s_cselect_b32 s13, s9, s44
	s_cselect_b32 s12, s8, s16
	v_lshl_add_u64 v[220:221], s[10:11], 0, v[148:149]
	s_add_i32 m0, s78, 0xc000
	ds_read_b128 v[188:191], v177
	ds_read_b128 v[192:195], v177 offset:1024
	ds_read_b128 v[196:199], v177 offset:2048
	ds_read_b128 v[200:203], v177 offset:3072
	ds_read_b128 v[204:207], v177 offset:4096
	ds_read_b128 v[208:211], v177 offset:5120
	ds_read_b128 v[212:215], v177 offset:6144
	ds_read_b128 v[216:219], v177 offset:7168
	global_load_lds_dwordx4 v[220:221], off
	v_lshl_add_u64 v[220:221], s[10:11], 0, v[150:151]
	s_add_i32 m0, s78, 0xe000
	s_nop 0
	global_load_lds_dwordx4 v[220:221], off
	s_waitcnt vmcnt(8)
	s_waitcnt lgkmcnt(0)
	s_barrier
	s_waitcnt lgkmcnt(0)
	v_mfma_f32_16x16x32_bf16 v[126:129], v[130:133], v[188:191], v[126:129]
	v_mfma_f32_16x16x32_bf16 v[122:125], v[156:159], v[188:191], v[122:125]
	v_mfma_f32_16x16x32_bf16 v[118:121], v[130:133], v[196:199], v[118:121]
	v_mfma_f32_16x16x32_bf16 v[114:117], v[156:159], v[196:199], v[114:117]
	v_mfma_f32_16x16x32_bf16 v[110:113], v[130:133], v[204:207], v[110:113]
	v_mfma_f32_16x16x32_bf16 v[106:109], v[156:159], v[204:207], v[106:109]
	v_mfma_f32_16x16x32_bf16 v[102:105], v[130:133], v[212:215], v[102:105]
	v_mfma_f32_16x16x32_bf16 v[98:101], v[156:159], v[212:215], v[98:101]
	v_mfma_f32_16x16x32_bf16 v[126:129], v[134:137], v[192:195], v[126:129]
	v_mfma_f32_16x16x32_bf16 v[122:125], v[160:163], v[192:195], v[122:125]
	v_mfma_f32_16x16x32_bf16 v[118:121], v[134:137], v[200:203], v[118:121]
	v_mfma_f32_16x16x32_bf16 v[114:117], v[160:163], v[200:203], v[114:117]
	v_mfma_f32_16x16x32_bf16 v[110:113], v[134:137], v[208:211], v[110:113]
	v_mfma_f32_16x16x32_bf16 v[106:109], v[160:163], v[208:211], v[106:109]
	v_mfma_f32_16x16x32_bf16 v[102:105], v[134:137], v[216:219], v[102:105]
	v_mfma_f32_16x16x32_bf16 v[98:101], v[160:163], v[216:219], v[98:101]
	v_mfma_f32_16x16x32_bf16 v[62:65], v[164:167], v[188:191], v[62:65]
	v_mfma_f32_16x16x32_bf16 v[58:61], v[180:183], v[188:191], v[58:61]
	v_mfma_f32_16x16x32_bf16 v[54:57], v[164:167], v[196:199], v[54:57]
	v_mfma_f32_16x16x32_bf16 v[50:53], v[180:183], v[196:199], v[50:53]
	v_mfma_f32_16x16x32_bf16 v[46:49], v[164:167], v[204:207], v[46:49]
	v_mfma_f32_16x16x32_bf16 v[42:45], v[180:183], v[204:207], v[42:45]
	v_mfma_f32_16x16x32_bf16 v[38:41], v[164:167], v[212:215], v[38:41]
	v_mfma_f32_16x16x32_bf16 v[34:37], v[180:183], v[212:215], v[34:37]
	v_mfma_f32_16x16x32_bf16 v[62:65], v[168:171], v[192:195], v[62:65]
	v_mfma_f32_16x16x32_bf16 v[58:61], v[184:187], v[192:195], v[58:61]
	v_mfma_f32_16x16x32_bf16 v[54:57], v[168:171], v[200:203], v[54:57]
	v_mfma_f32_16x16x32_bf16 v[50:53], v[184:187], v[200:203], v[50:53]
	v_mfma_f32_16x16x32_bf16 v[46:49], v[168:171], v[208:211], v[46:49]
	v_mfma_f32_16x16x32_bf16 v[42:45], v[184:187], v[208:211], v[42:45]
	v_mfma_f32_16x16x32_bf16 v[38:41], v[168:171], v[216:219], v[38:41]
	v_mfma_f32_16x16x32_bf16 v[34:37], v[184:187], v[216:219], v[34:37]
	s_barrier
	s_add_i32 s46, s87, s61
	v_lshl_add_u64 v[220:221], s[12:13], 0, v[140:141]
	s_mov_b32 m0, s46
	ds_read_b128 v[188:191], v177 offset:16384
	ds_read_b128 v[192:195], v177 offset:17408
	ds_read_b128 v[196:199], v177 offset:18432
	ds_read_b128 v[200:203], v177 offset:19456
	ds_read_b128 v[204:207], v177 offset:20480
	ds_read_b128 v[208:211], v177 offset:21504
	ds_read_b128 v[212:215], v177 offset:22528
	ds_read_b128 v[216:219], v177 offset:23552
	global_load_lds_dwordx4 v[220:221], off
	s_add_i32 m0, s46, 0x2000
	s_add_u32 s46, s12, 0x40000
	v_lshl_add_u64 v[222:223], s[12:13], 0, v[144:145]
	s_addc_u32 s47, s13, 0
	s_add_i32 s55, s88, s61
	global_load_lds_dwordx4 v[222:223], off
	v_lshl_add_u64 v[224:225], s[46:47], 0, v[140:141]
	s_mov_b32 m0, s55
	v_lshl_add_u64 v[226:227], s[62:63], 0, v[142:143]
	global_load_lds_dwordx4 v[224:225], off
	v_lshl_add_u64 v[224:225], s[46:47], 0, v[144:145]
	s_add_i32 m0, s55, 0x2000
	s_nop 0
	global_load_lds_dwordx4 v[224:225], off
	v_lshl_add_u64 v[224:225], s[62:63], 0, v[138:139]
	s_mov_b32 m0, s78
	s_nop 0
	global_load_lds_dwordx4 v[224:225], off
	s_mov_b32 m0, s79
	s_nop 0
	global_load_lds_dwordx4 v[226:227], off
	s_waitcnt vmcnt(8)
	s_waitcnt lgkmcnt(0)
	s_barrier
	s_waitcnt lgkmcnt(0)
	v_mfma_f32_16x16x32_bf16 v[94:97], v[130:133], v[188:191], v[94:97]
	v_mfma_f32_16x16x32_bf16 v[90:93], v[156:159], v[188:191], v[90:93]
	v_mfma_f32_16x16x32_bf16 v[86:89], v[130:133], v[196:199], v[86:89]
	v_mfma_f32_16x16x32_bf16 v[82:85], v[156:159], v[196:199], v[82:85]
	v_mfma_f32_16x16x32_bf16 v[78:81], v[130:133], v[204:207], v[78:81]
	v_mfma_f32_16x16x32_bf16 v[74:77], v[156:159], v[204:207], v[74:77]
	v_mfma_f32_16x16x32_bf16 v[70:73], v[130:133], v[212:215], v[70:73]
	v_mfma_f32_16x16x32_bf16 v[66:69], v[156:159], v[212:215], v[66:69]
	v_mfma_f32_16x16x32_bf16 v[94:97], v[134:137], v[192:195], v[94:97]
	v_mfma_f32_16x16x32_bf16 v[90:93], v[160:163], v[192:195], v[90:93]
	v_mfma_f32_16x16x32_bf16 v[86:89], v[134:137], v[200:203], v[86:89]
	v_mfma_f32_16x16x32_bf16 v[82:85], v[160:163], v[200:203], v[82:85]
	v_mfma_f32_16x16x32_bf16 v[78:81], v[134:137], v[208:211], v[78:81]
	v_mfma_f32_16x16x32_bf16 v[74:77], v[160:163], v[208:211], v[74:77]
	v_mfma_f32_16x16x32_bf16 v[70:73], v[134:137], v[216:219], v[70:73]
	v_mfma_f32_16x16x32_bf16 v[66:69], v[160:163], v[216:219], v[66:69]
	v_mfma_f32_16x16x32_bf16 v[30:33], v[164:167], v[188:191], v[30:33]
	v_mfma_f32_16x16x32_bf16 v[26:29], v[180:183], v[188:191], v[26:29]
	v_mfma_f32_16x16x32_bf16 v[22:25], v[164:167], v[196:199], v[22:25]
	v_mfma_f32_16x16x32_bf16 v[18:21], v[180:183], v[196:199], v[18:21]
	v_mfma_f32_16x16x32_bf16 v[14:17], v[164:167], v[204:207], v[14:17]
	v_mfma_f32_16x16x32_bf16 v[10:13], v[180:183], v[204:207], v[10:13]
	v_mfma_f32_16x16x32_bf16 v[6:9], v[164:167], v[212:215], v[6:9]
	v_mfma_f32_16x16x32_bf16 v[2:5], v[180:183], v[212:215], v[2:5]
	v_mfma_f32_16x16x32_bf16 v[30:33], v[168:171], v[192:195], v[30:33]
	v_mfma_f32_16x16x32_bf16 v[26:29], v[184:187], v[192:195], v[26:29]
	v_mfma_f32_16x16x32_bf16 v[22:25], v[168:171], v[200:203], v[22:25]
	v_mfma_f32_16x16x32_bf16 v[18:21], v[184:187], v[200:203], v[18:21]
	v_mfma_f32_16x16x32_bf16 v[14:17], v[168:171], v[208:211], v[14:17]
	v_mfma_f32_16x16x32_bf16 v[10:13], v[184:187], v[208:211], v[10:13]
	v_mfma_f32_16x16x32_bf16 v[6:9], v[168:171], v[216:219], v[6:9]
	v_mfma_f32_16x16x32_bf16 v[2:5], v[184:187], v[216:219], v[2:5]
	s_barrier
	s_add_i32 s55, 0, 0x18000
	v_add_u32_e32 v146, s55, v173
	s_add_i32 s74, 0, 0x1c000
	ds_read_b128 v[130:133], v146
	ds_read_b128 v[134:137], v146 offset:1024
	ds_read_b128 v[156:159], v146 offset:2048
	ds_read_b128 v[160:163], v146 offset:3072
	v_add_u32_e32 v146, s74, v173
	ds_read_b128 v[164:167], v146
	ds_read_b128 v[168:171], v146 offset:1024
	ds_read_b128 v[180:183], v146 offset:2048
	ds_read_b128 v[184:187], v146 offset:3072
	s_add_u32 s46, s62, 0x40000
	s_addc_u32 s47, s63, 0
	s_mov_b32 m0, s80
	v_lshl_add_u64 v[228:229], s[46:47], 0, v[138:139]
	ds_read_b128 v[188:191], v177 offset:32768
	ds_read_b128 v[192:195], v177 offset:33792
	ds_read_b128 v[196:199], v177 offset:34816
	ds_read_b128 v[200:203], v177 offset:35840
	ds_read_b128 v[204:207], v177 offset:36864
	ds_read_b128 v[208:211], v177 offset:37888
	ds_read_b128 v[212:215], v177 offset:38912
	ds_read_b128 v[216:219], v177 offset:39936
	global_load_lds_dwordx4 v[228:229], off
	v_lshl_add_u64 v[228:229], s[46:47], 0, v[142:143]
	s_mov_b32 m0, s81
	s_nop 0
	global_load_lds_dwordx4 v[228:229], off
	s_waitcnt vmcnt(8)
	s_waitcnt lgkmcnt(0)
	s_barrier
	s_waitcnt lgkmcnt(0)
	v_mfma_f32_16x16x32_bf16 v[126:129], v[130:133], v[188:191], v[126:129]
	v_mfma_f32_16x16x32_bf16 v[122:125], v[156:159], v[188:191], v[122:125]
	v_mfma_f32_16x16x32_bf16 v[118:121], v[130:133], v[196:199], v[118:121]
	v_mfma_f32_16x16x32_bf16 v[114:117], v[156:159], v[196:199], v[114:117]
	v_mfma_f32_16x16x32_bf16 v[110:113], v[130:133], v[204:207], v[110:113]
	v_mfma_f32_16x16x32_bf16 v[106:109], v[156:159], v[204:207], v[106:109]
	v_mfma_f32_16x16x32_bf16 v[102:105], v[130:133], v[212:215], v[102:105]
	v_mfma_f32_16x16x32_bf16 v[98:101], v[156:159], v[212:215], v[98:101]
	v_mfma_f32_16x16x32_bf16 v[126:129], v[134:137], v[192:195], v[126:129]
	v_mfma_f32_16x16x32_bf16 v[122:125], v[160:163], v[192:195], v[122:125]
	v_mfma_f32_16x16x32_bf16 v[118:121], v[134:137], v[200:203], v[118:121]
	v_mfma_f32_16x16x32_bf16 v[114:117], v[160:163], v[200:203], v[114:117]
	v_mfma_f32_16x16x32_bf16 v[110:113], v[134:137], v[208:211], v[110:113]
	v_mfma_f32_16x16x32_bf16 v[106:109], v[160:163], v[208:211], v[106:109]
	v_mfma_f32_16x16x32_bf16 v[102:105], v[134:137], v[216:219], v[102:105]
	v_mfma_f32_16x16x32_bf16 v[98:101], v[160:163], v[216:219], v[98:101]
	v_mfma_f32_16x16x32_bf16 v[62:65], v[164:167], v[188:191], v[62:65]
	v_mfma_f32_16x16x32_bf16 v[58:61], v[180:183], v[188:191], v[58:61]
	v_mfma_f32_16x16x32_bf16 v[54:57], v[164:167], v[196:199], v[54:57]
	v_mfma_f32_16x16x32_bf16 v[50:53], v[180:183], v[196:199], v[50:53]
	v_mfma_f32_16x16x32_bf16 v[46:49], v[164:167], v[204:207], v[46:49]
	v_mfma_f32_16x16x32_bf16 v[42:45], v[180:183], v[204:207], v[42:45]
	v_mfma_f32_16x16x32_bf16 v[38:41], v[164:167], v[212:215], v[38:41]
	v_mfma_f32_16x16x32_bf16 v[34:37], v[180:183], v[212:215], v[34:37]
	v_mfma_f32_16x16x32_bf16 v[62:65], v[168:171], v[192:195], v[62:65]
	v_mfma_f32_16x16x32_bf16 v[58:61], v[184:187], v[192:195], v[58:61]
	v_mfma_f32_16x16x32_bf16 v[54:57], v[168:171], v[200:203], v[54:57]
	v_mfma_f32_16x16x32_bf16 v[50:53], v[184:187], v[200:203], v[50:53]
	v_mfma_f32_16x16x32_bf16 v[46:49], v[168:171], v[208:211], v[46:49]
	v_mfma_f32_16x16x32_bf16 v[42:45], v[184:187], v[208:211], v[42:45]
	v_mfma_f32_16x16x32_bf16 v[38:41], v[168:171], v[216:219], v[38:41]
	v_mfma_f32_16x16x32_bf16 v[34:37], v[184:187], v[216:219], v[34:37]
	s_barrier
	s_add_i32 s46, s55, s61
	v_lshl_add_u64 v[220:221], v[220:221], 0, s[38:39]
	s_mov_b32 m0, s46
	ds_read_b128 v[188:191], v177 offset:49152
	ds_read_b128 v[192:195], v177 offset:50176
	ds_read_b128 v[196:199], v177 offset:51200
	ds_read_b128 v[200:203], v177 offset:52224
	ds_read_b128 v[204:207], v177 offset:53248
	ds_read_b128 v[208:211], v177 offset:54272
	ds_read_b128 v[212:215], v177 offset:55296
	ds_read_b128 v[216:219], v177 offset:56320
	global_load_lds_dwordx4 v[220:221], off
	s_add_i32 m0, s46, 0x2000
	s_add_u32 s12, s12, 0x40080
	v_lshl_add_u64 v[220:221], v[222:223], 0, s[38:39]
	s_addc_u32 s13, s13, 0
	s_add_i32 s46, s74, s61
	global_load_lds_dwordx4 v[220:221], off
	v_lshl_add_u64 v[220:221], s[12:13], 0, v[140:141]
	s_mov_b32 m0, s46
	s_nop 0
	global_load_lds_dwordx4 v[220:221], off
	v_lshl_add_u64 v[220:221], s[12:13], 0, v[144:145]
	s_add_i32 m0, s46, 0x2000
	s_nop 0
	global_load_lds_dwordx4 v[220:221], off
	v_lshl_add_u64 v[220:221], v[224:225], 0, s[38:39]
	s_mov_b32 m0, s84
	s_nop 0
	global_load_lds_dwordx4 v[220:221], off
	v_lshl_add_u64 v[220:221], v[226:227], 0, s[38:39]
	s_mov_b32 m0, s85
	s_nop 0
	global_load_lds_dwordx4 v[220:221], off
	s_waitcnt vmcnt(8)
	s_waitcnt lgkmcnt(0)
	s_barrier
	s_waitcnt lgkmcnt(0)
	v_mfma_f32_16x16x32_bf16 v[94:97], v[130:133], v[188:191], v[94:97]
	v_mfma_f32_16x16x32_bf16 v[90:93], v[156:159], v[188:191], v[90:93]
	v_mfma_f32_16x16x32_bf16 v[86:89], v[130:133], v[196:199], v[86:89]
	v_mfma_f32_16x16x32_bf16 v[82:85], v[156:159], v[196:199], v[82:85]
	v_mfma_f32_16x16x32_bf16 v[78:81], v[130:133], v[204:207], v[78:81]
	v_mfma_f32_16x16x32_bf16 v[74:77], v[156:159], v[204:207], v[74:77]
	v_mfma_f32_16x16x32_bf16 v[70:73], v[130:133], v[212:215], v[70:73]
	v_mfma_f32_16x16x32_bf16 v[66:69], v[156:159], v[212:215], v[66:69]
	v_mfma_f32_16x16x32_bf16 v[94:97], v[134:137], v[192:195], v[94:97]
	v_mfma_f32_16x16x32_bf16 v[90:93], v[160:163], v[192:195], v[90:93]
	v_mfma_f32_16x16x32_bf16 v[86:89], v[134:137], v[200:203], v[86:89]
	v_mfma_f32_16x16x32_bf16 v[82:85], v[160:163], v[200:203], v[82:85]
	v_mfma_f32_16x16x32_bf16 v[78:81], v[134:137], v[208:211], v[78:81]
	v_mfma_f32_16x16x32_bf16 v[74:77], v[160:163], v[208:211], v[74:77]
	v_mfma_f32_16x16x32_bf16 v[70:73], v[134:137], v[216:219], v[70:73]
	v_mfma_f32_16x16x32_bf16 v[66:69], v[160:163], v[216:219], v[66:69]
	v_mfma_f32_16x16x32_bf16 v[30:33], v[164:167], v[188:191], v[30:33]
	v_mfma_f32_16x16x32_bf16 v[26:29], v[180:183], v[188:191], v[26:29]
	v_mfma_f32_16x16x32_bf16 v[22:25], v[164:167], v[196:199], v[22:25]
	v_mfma_f32_16x16x32_bf16 v[18:21], v[180:183], v[196:199], v[18:21]
	v_mfma_f32_16x16x32_bf16 v[14:17], v[164:167], v[204:207], v[14:17]
	v_mfma_f32_16x16x32_bf16 v[10:13], v[180:183], v[204:207], v[10:13]
	v_mfma_f32_16x16x32_bf16 v[6:9], v[164:167], v[212:215], v[6:9]
	v_mfma_f32_16x16x32_bf16 v[2:5], v[180:183], v[212:215], v[2:5]
	v_mfma_f32_16x16x32_bf16 v[30:33], v[168:171], v[192:195], v[30:33]
	v_mfma_f32_16x16x32_bf16 v[26:29], v[184:187], v[192:195], v[26:29]
	v_mfma_f32_16x16x32_bf16 v[22:25], v[168:171], v[200:203], v[22:25]
	v_mfma_f32_16x16x32_bf16 v[18:21], v[184:187], v[200:203], v[18:21]
	v_mfma_f32_16x16x32_bf16 v[14:17], v[168:171], v[208:211], v[14:17]
	v_mfma_f32_16x16x32_bf16 v[10:13], v[184:187], v[208:211], v[10:13]
	v_mfma_f32_16x16x32_bf16 v[6:9], v[168:171], v[216:219], v[6:9]
	v_mfma_f32_16x16x32_bf16 v[2:5], v[184:187], v[216:219], v[2:5]
	s_barrier
	s_add_i32 s45, s45, 2
	s_add_u32 s10, s10, 0x100
	s_addc_u32 s11, s11, 0
	s_add_u32 s16, s16, 0x100
	s_addc_u32 s44, s44, 0
	s_cmp_gt_u32 s45, 13
	s_cbranch_scc0 .LBB0_590
	s_and_b64 vcc, exec, s[40:41]
	s_cbranch_vccz .LBB0_593
	s_barrier

.LBB0_1097:
	v_add_u32_e32 v158, s79, v161
	ds_read_b128 v[146:149], v158
	ds_read_b128 v[150:153], v158 offset:1024
	ds_read_b128 v[154:157], v158 offset:2048
	ds_read_b128 v[164:167], v158 offset:3072
	v_add_u32_e32 v158, s80, v161
	ds_read_b128 v[168:171], v158
	ds_read_b128 v[172:175], v158 offset:1024
	ds_read_b128 v[176:179], v158 offset:2048
	ds_read_b128 v[180:183], v158 offset:3072
	s_add_u32 s45, s48, 0xfffc0080
	s_addc_u32 s47, s49, -1
	s_cmp_eq_u32 s44, 12
	s_cselect_b32 s53, s41, s47
	s_cselect_b32 s52, s40, s45
	s_cselect_b32 s51, s43, s35
	s_cselect_b32 s50, s42, s31
	v_lshl_add_u64 v[158:159], s[48:49], 0, v[138:139]
	s_add_i32 m0, s58, 0xc000
	ds_read_b128 v[184:187], v163
	ds_read_b128 v[188:191], v163 offset:1024
	ds_read_b128 v[192:195], v163 offset:2048
	ds_read_b128 v[196:199], v163 offset:3072
	ds_read_b128 v[200:203], v163 offset:4096
	ds_read_b128 v[204:207], v163 offset:5120
	ds_read_b128 v[208:211], v163 offset:6144
	ds_read_b128 v[212:215], v163 offset:7168
	global_load_lds_dwordx4 v[158:159], off
	v_lshl_add_u64 v[158:159], s[48:49], 0, v[140:141]
	s_add_i32 m0, s58, 0xe000
	s_nop 0
	global_load_lds_dwordx4 v[158:159], off
	s_waitcnt vmcnt(8)
	s_waitcnt lgkmcnt(0)
	s_barrier
	s_waitcnt lgkmcnt(0)
	v_mfma_f32_16x16x32_bf16 v[126:129], v[146:149], v[184:187], v[126:129]
	v_mfma_f32_16x16x32_bf16 v[122:125], v[154:157], v[184:187], v[122:125]
	v_mfma_f32_16x16x32_bf16 v[118:121], v[146:149], v[192:195], v[118:121]
	v_mfma_f32_16x16x32_bf16 v[114:117], v[154:157], v[192:195], v[114:117]
	v_mfma_f32_16x16x32_bf16 v[110:113], v[146:149], v[200:203], v[110:113]
	v_mfma_f32_16x16x32_bf16 v[106:109], v[154:157], v[200:203], v[106:109]
	v_mfma_f32_16x16x32_bf16 v[102:105], v[146:149], v[208:211], v[102:105]
	v_mfma_f32_16x16x32_bf16 v[98:101], v[154:157], v[208:211], v[98:101]
	v_mfma_f32_16x16x32_bf16 v[126:129], v[150:153], v[188:191], v[126:129]
	v_mfma_f32_16x16x32_bf16 v[122:125], v[164:167], v[188:191], v[122:125]
	v_mfma_f32_16x16x32_bf16 v[118:121], v[150:153], v[196:199], v[118:121]
	v_mfma_f32_16x16x32_bf16 v[114:117], v[164:167], v[196:199], v[114:117]
	v_mfma_f32_16x16x32_bf16 v[110:113], v[150:153], v[204:207], v[110:113]
	v_mfma_f32_16x16x32_bf16 v[106:109], v[164:167], v[204:207], v[106:109]
	v_mfma_f32_16x16x32_bf16 v[102:105], v[150:153], v[212:215], v[102:105]
	v_mfma_f32_16x16x32_bf16 v[98:101], v[164:167], v[212:215], v[98:101]
	v_mfma_f32_16x16x32_bf16 v[94:97], v[168:171], v[184:187], v[94:97]
	v_mfma_f32_16x16x32_bf16 v[90:93], v[176:179], v[184:187], v[90:93]
	v_mfma_f32_16x16x32_bf16 v[86:89], v[168:171], v[192:195], v[86:89]
	v_mfma_f32_16x16x32_bf16 v[82:85], v[176:179], v[192:195], v[82:85]
	v_mfma_f32_16x16x32_bf16 v[78:81], v[168:171], v[200:203], v[78:81]
	v_mfma_f32_16x16x32_bf16 v[74:77], v[176:179], v[200:203], v[74:77]
	v_mfma_f32_16x16x32_bf16 v[70:73], v[168:171], v[208:211], v[70:73]
	v_mfma_f32_16x16x32_bf16 v[66:69], v[176:179], v[208:211], v[66:69]
	v_mfma_f32_16x16x32_bf16 v[94:97], v[172:175], v[188:191], v[94:97]
	v_mfma_f32_16x16x32_bf16 v[90:93], v[180:183], v[188:191], v[90:93]
	v_mfma_f32_16x16x32_bf16 v[86:89], v[172:175], v[196:199], v[86:89]
	v_mfma_f32_16x16x32_bf16 v[82:85], v[180:183], v[196:199], v[82:85]
	v_mfma_f32_16x16x32_bf16 v[78:81], v[172:175], v[204:207], v[78:81]
	v_mfma_f32_16x16x32_bf16 v[74:77], v[180:183], v[204:207], v[74:77]
	v_mfma_f32_16x16x32_bf16 v[70:73], v[172:175], v[212:215], v[70:73]
	v_mfma_f32_16x16x32_bf16 v[66:69], v[180:183], v[212:215], v[66:69]
	s_barrier
	s_add_i32 s45, s79, s57
	v_lshl_add_u64 v[158:159], s[50:51], 0, v[132:133]
	s_mov_b32 m0, s45
	ds_read_b128 v[184:187], v163 offset:16384
	ds_read_b128 v[188:191], v163 offset:17408
	ds_read_b128 v[192:195], v163 offset:18432
	ds_read_b128 v[196:199], v163 offset:19456
	ds_read_b128 v[200:203], v163 offset:20480
	ds_read_b128 v[204:207], v163 offset:21504
	ds_read_b128 v[208:211], v163 offset:22528
	ds_read_b128 v[212:215], v163 offset:23552
	global_load_lds_dwordx4 v[158:159], off
	s_add_i32 m0, s45, 0x2000
	s_add_u32 s84, s50, 0x40000
	v_lshl_add_u64 v[216:217], s[50:51], 0, v[136:137]
	s_addc_u32 s85, s51, 0
	s_add_i32 s45, s80, s57
	global_load_lds_dwordx4 v[216:217], off
	v_lshl_add_u64 v[218:219], s[84:85], 0, v[132:133]
	s_mov_b32 m0, s45
	v_lshl_add_u64 v[220:221], s[52:53], 0, v[134:135]
	global_load_lds_dwordx4 v[218:219], off
	v_lshl_add_u64 v[218:219], s[84:85], 0, v[136:137]
	s_add_i32 m0, s45, 0x2000
	s_nop 0
	global_load_lds_dwordx4 v[218:219], off
	v_lshl_add_u64 v[218:219], s[52:53], 0, v[130:131]
	s_mov_b32 m0, s58
	s_nop 0
	global_load_lds_dwordx4 v[218:219], off
	s_mov_b32 m0, s59
	s_nop 0
	global_load_lds_dwordx4 v[220:221], off
	s_waitcnt vmcnt(8)
	s_waitcnt lgkmcnt(0)
	s_barrier
	s_waitcnt lgkmcnt(0)
	v_mfma_f32_16x16x32_bf16 v[62:65], v[146:149], v[184:187], v[62:65]
	v_mfma_f32_16x16x32_bf16 v[58:61], v[154:157], v[184:187], v[58:61]
	v_mfma_f32_16x16x32_bf16 v[54:57], v[146:149], v[192:195], v[54:57]
	v_mfma_f32_16x16x32_bf16 v[50:53], v[154:157], v[192:195], v[50:53]
	v_mfma_f32_16x16x32_bf16 v[46:49], v[146:149], v[200:203], v[46:49]
	v_mfma_f32_16x16x32_bf16 v[42:45], v[154:157], v[200:203], v[42:45]
	v_mfma_f32_16x16x32_bf16 v[38:41], v[146:149], v[208:211], v[38:41]
	v_mfma_f32_16x16x32_bf16 v[34:37], v[154:157], v[208:211], v[34:37]
	v_mfma_f32_16x16x32_bf16 v[62:65], v[150:153], v[188:191], v[62:65]
	v_mfma_f32_16x16x32_bf16 v[58:61], v[164:167], v[188:191], v[58:61]
	v_mfma_f32_16x16x32_bf16 v[54:57], v[150:153], v[196:199], v[54:57]
	v_mfma_f32_16x16x32_bf16 v[50:53], v[164:167], v[196:199], v[50:53]
	v_mfma_f32_16x16x32_bf16 v[46:49], v[150:153], v[204:207], v[46:49]
	v_mfma_f32_16x16x32_bf16 v[42:45], v[164:167], v[204:207], v[42:45]
	v_mfma_f32_16x16x32_bf16 v[38:41], v[150:153], v[212:215], v[38:41]
	v_mfma_f32_16x16x32_bf16 v[34:37], v[164:167], v[212:215], v[34:37]
	v_mfma_f32_16x16x32_bf16 v[30:33], v[168:171], v[184:187], v[30:33]
	v_mfma_f32_16x16x32_bf16 v[26:29], v[176:179], v[184:187], v[26:29]
	v_mfma_f32_16x16x32_bf16 v[22:25], v[168:171], v[192:195], v[22:25]
	v_mfma_f32_16x16x32_bf16 v[18:21], v[176:179], v[192:195], v[18:21]
	v_mfma_f32_16x16x32_bf16 v[14:17], v[168:171], v[200:203], v[14:17]
	v_mfma_f32_16x16x32_bf16 v[10:13], v[176:179], v[200:203], v[10:13]
	v_mfma_f32_16x16x32_bf16 v[6:9], v[168:171], v[208:211], v[6:9]
	v_mfma_f32_16x16x32_bf16 v[2:5], v[176:179], v[208:211], v[2:5]
	v_mfma_f32_16x16x32_bf16 v[30:33], v[172:175], v[188:191], v[30:33]
	v_mfma_f32_16x16x32_bf16 v[26:29], v[180:183], v[188:191], v[26:29]
	v_mfma_f32_16x16x32_bf16 v[22:25], v[172:175], v[196:199], v[22:25]
	v_mfma_f32_16x16x32_bf16 v[18:21], v[180:183], v[196:199], v[18:21]
	v_mfma_f32_16x16x32_bf16 v[14:17], v[172:175], v[204:207], v[14:17]
	v_mfma_f32_16x16x32_bf16 v[10:13], v[180:183], v[204:207], v[10:13]
	v_mfma_f32_16x16x32_bf16 v[6:9], v[172:175], v[212:215], v[6:9]
	v_mfma_f32_16x16x32_bf16 v[2:5], v[180:183], v[212:215], v[2:5]
	s_barrier
	s_add_i32 s45, 0, 0x18000
	s_add_i32 s47, 0, 0x1c000
	v_add_u32_e32 v164, s45, v161
	v_add_u32_e32 v180, s47, v161
	ds_read_b128 v[146:149], v164
	ds_read_b128 v[150:153], v164 offset:1024
	ds_read_b128 v[154:157], v164 offset:2048
	ds_read_b128 v[164:167], v164 offset:3072
	ds_read_b128 v[168:171], v180
	ds_read_b128 v[172:175], v180 offset:1024
	ds_read_b128 v[176:179], v180 offset:2048
	ds_read_b128 v[180:183], v180 offset:3072
	s_add_u32 s52, s52, 0x40000
	s_addc_u32 s53, s53, 0
	s_mov_b32 m0, s60
	v_lshl_add_u64 v[222:223], s[52:53], 0, v[130:131]
	ds_read_b128 v[184:187], v163 offset:32768
	ds_read_b128 v[188:191], v163 offset:33792
	ds_read_b128 v[192:195], v163 offset:34816
	ds_read_b128 v[196:199], v163 offset:35840
	ds_read_b128 v[200:203], v163 offset:36864
	ds_read_b128 v[204:207], v163 offset:37888
	ds_read_b128 v[208:211], v163 offset:38912
	ds_read_b128 v[212:215], v163 offset:39936
	global_load_lds_dwordx4 v[222:223], off
	v_lshl_add_u64 v[222:223], s[52:53], 0, v[134:135]
	s_mov_b32 m0, s61
	s_nop 0
	global_load_lds_dwordx4 v[222:223], off
	s_waitcnt vmcnt(8)
	s_waitcnt lgkmcnt(0)
	s_barrier
	s_waitcnt lgkmcnt(0)
	v_mfma_f32_16x16x32_bf16 v[126:129], v[146:149], v[184:187], v[126:129]
	v_mfma_f32_16x16x32_bf16 v[122:125], v[154:157], v[184:187], v[122:125]
	v_mfma_f32_16x16x32_bf16 v[118:121], v[146:149], v[192:195], v[118:121]
	v_mfma_f32_16x16x32_bf16 v[114:117], v[154:157], v[192:195], v[114:117]
	v_mfma_f32_16x16x32_bf16 v[110:113], v[146:149], v[200:203], v[110:113]
	v_mfma_f32_16x16x32_bf16 v[106:109], v[154:157], v[200:203], v[106:109]
	v_mfma_f32_16x16x32_bf16 v[102:105], v[146:149], v[208:211], v[102:105]
	v_mfma_f32_16x16x32_bf16 v[98:101], v[154:157], v[208:211], v[98:101]
	v_mfma_f32_16x16x32_bf16 v[126:129], v[150:153], v[188:191], v[126:129]
	v_mfma_f32_16x16x32_bf16 v[122:125], v[164:167], v[188:191], v[122:125]
	v_mfma_f32_16x16x32_bf16 v[118:121], v[150:153], v[196:199], v[118:121]
	v_mfma_f32_16x16x32_bf16 v[114:117], v[164:167], v[196:199], v[114:117]
	v_mfma_f32_16x16x32_bf16 v[110:113], v[150:153], v[204:207], v[110:113]
	v_mfma_f32_16x16x32_bf16 v[106:109], v[164:167], v[204:207], v[106:109]
	v_mfma_f32_16x16x32_bf16 v[102:105], v[150:153], v[212:215], v[102:105]
	v_mfma_f32_16x16x32_bf16 v[98:101], v[164:167], v[212:215], v[98:101]
	v_mfma_f32_16x16x32_bf16 v[94:97], v[168:171], v[184:187], v[94:97]
	v_mfma_f32_16x16x32_bf16 v[90:93], v[176:179], v[184:187], v[90:93]
	v_mfma_f32_16x16x32_bf16 v[86:89], v[168:171], v[192:195], v[86:89]
	v_mfma_f32_16x16x32_bf16 v[82:85], v[176:179], v[192:195], v[82:85]
	v_mfma_f32_16x16x32_bf16 v[78:81], v[168:171], v[200:203], v[78:81]
	v_mfma_f32_16x16x32_bf16 v[74:77], v[176:179], v[200:203], v[74:77]
	v_mfma_f32_16x16x32_bf16 v[70:73], v[168:171], v[208:211], v[70:73]
	v_mfma_f32_16x16x32_bf16 v[66:69], v[176:179], v[208:211], v[66:69]
	v_mfma_f32_16x16x32_bf16 v[94:97], v[172:175], v[188:191], v[94:97]
	v_mfma_f32_16x16x32_bf16 v[90:93], v[180:183], v[188:191], v[90:93]
	v_mfma_f32_16x16x32_bf16 v[86:89], v[172:175], v[196:199], v[86:89]
	v_mfma_f32_16x16x32_bf16 v[82:85], v[180:183], v[196:199], v[82:85]
	v_mfma_f32_16x16x32_bf16 v[78:81], v[172:175], v[204:207], v[78:81]
	v_mfma_f32_16x16x32_bf16 v[74:77], v[180:183], v[204:207], v[74:77]
	v_mfma_f32_16x16x32_bf16 v[70:73], v[172:175], v[212:215], v[70:73]
	v_mfma_f32_16x16x32_bf16 v[66:69], v[180:183], v[212:215], v[66:69]
	s_barrier
	s_add_i32 s45, s45, s57
	v_lshl_add_u64 v[158:159], v[158:159], 0, s[18:19]
	s_mov_b32 m0, s45
	ds_read_b128 v[184:187], v163 offset:49152
	ds_read_b128 v[188:191], v163 offset:50176
	ds_read_b128 v[192:195], v163 offset:51200
	ds_read_b128 v[196:199], v163 offset:52224
	ds_read_b128 v[200:203], v163 offset:53248
	ds_read_b128 v[204:207], v163 offset:54272
	ds_read_b128 v[208:211], v163 offset:55296
	ds_read_b128 v[212:215], v163 offset:56320
	global_load_lds_dwordx4 v[158:159], off
	s_add_i32 m0, s45, 0x2000
	s_add_u32 s50, s50, 0x40080
	v_lshl_add_u64 v[158:159], v[216:217], 0, s[18:19]
	s_addc_u32 s51, s51, 0
	s_add_i32 s45, s47, s57
	global_load_lds_dwordx4 v[158:159], off
	v_lshl_add_u64 v[158:159], s[50:51], 0, v[132:133]
	s_mov_b32 m0, s45
	s_nop 0
	global_load_lds_dwordx4 v[158:159], off
	v_lshl_add_u64 v[158:159], s[50:51], 0, v[136:137]
	s_add_i32 m0, s45, 0x2000
	s_nop 0
	global_load_lds_dwordx4 v[158:159], off
	v_lshl_add_u64 v[158:159], v[218:219], 0, s[18:19]
	s_mov_b32 m0, s77
	s_nop 0
	global_load_lds_dwordx4 v[158:159], off
	v_lshl_add_u64 v[158:159], v[220:221], 0, s[18:19]
	s_mov_b32 m0, s78
	s_nop 0
	global_load_lds_dwordx4 v[158:159], off
	s_waitcnt vmcnt(8)
	s_waitcnt lgkmcnt(0)
	s_barrier
	s_waitcnt lgkmcnt(0)
	v_mfma_f32_16x16x32_bf16 v[62:65], v[146:149], v[184:187], v[62:65]
	v_mfma_f32_16x16x32_bf16 v[58:61], v[154:157], v[184:187], v[58:61]
	v_mfma_f32_16x16x32_bf16 v[54:57], v[146:149], v[192:195], v[54:57]
	v_mfma_f32_16x16x32_bf16 v[50:53], v[154:157], v[192:195], v[50:53]
	v_mfma_f32_16x16x32_bf16 v[46:49], v[146:149], v[200:203], v[46:49]
	v_mfma_f32_16x16x32_bf16 v[42:45], v[154:157], v[200:203], v[42:45]
	v_mfma_f32_16x16x32_bf16 v[38:41], v[146:149], v[208:211], v[38:41]
	v_mfma_f32_16x16x32_bf16 v[34:37], v[154:157], v[208:211], v[34:37]
	v_mfma_f32_16x16x32_bf16 v[62:65], v[150:153], v[188:191], v[62:65]
	v_mfma_f32_16x16x32_bf16 v[58:61], v[164:167], v[188:191], v[58:61]
	v_mfma_f32_16x16x32_bf16 v[54:57], v[150:153], v[196:199], v[54:57]
	v_mfma_f32_16x16x32_bf16 v[50:53], v[164:167], v[196:199], v[50:53]
	v_mfma_f32_16x16x32_bf16 v[46:49], v[150:153], v[204:207], v[46:49]
	v_mfma_f32_16x16x32_bf16 v[42:45], v[164:167], v[204:207], v[42:45]
	v_mfma_f32_16x16x32_bf16 v[38:41], v[150:153], v[212:215], v[38:41]
	v_mfma_f32_16x16x32_bf16 v[34:37], v[164:167], v[212:215], v[34:37]
	v_mfma_f32_16x16x32_bf16 v[30:33], v[168:171], v[184:187], v[30:33]
	v_mfma_f32_16x16x32_bf16 v[26:29], v[176:179], v[184:187], v[26:29]
	v_mfma_f32_16x16x32_bf16 v[22:25], v[168:171], v[192:195], v[22:25]
	v_mfma_f32_16x16x32_bf16 v[18:21], v[176:179], v[192:195], v[18:21]
	v_mfma_f32_16x16x32_bf16 v[14:17], v[168:171], v[200:203], v[14:17]
	v_mfma_f32_16x16x32_bf16 v[10:13], v[176:179], v[200:203], v[10:13]
	v_mfma_f32_16x16x32_bf16 v[6:9], v[168:171], v[208:211], v[6:9]
	v_mfma_f32_16x16x32_bf16 v[2:5], v[176:179], v[208:211], v[2:5]
	v_mfma_f32_16x16x32_bf16 v[30:33], v[172:175], v[188:191], v[30:33]
	v_mfma_f32_16x16x32_bf16 v[26:29], v[180:183], v[188:191], v[26:29]
	v_mfma_f32_16x16x32_bf16 v[22:25], v[172:175], v[196:199], v[22:25]
	v_mfma_f32_16x16x32_bf16 v[18:21], v[180:183], v[196:199], v[18:21]
	v_mfma_f32_16x16x32_bf16 v[14:17], v[172:175], v[204:207], v[14:17]
	v_mfma_f32_16x16x32_bf16 v[10:13], v[180:183], v[204:207], v[10:13]
	v_mfma_f32_16x16x32_bf16 v[6:9], v[172:175], v[212:215], v[6:9]
	v_mfma_f32_16x16x32_bf16 v[2:5], v[180:183], v[212:215], v[2:5]
	s_barrier
	s_add_i32 s44, s44, 2
	s_add_u32 s48, s48, 0x100
	s_addc_u32 s49, s49, 0
	s_add_u32 s31, s31, 0x100
	s_addc_u32 s35, s35, 0
	s_cmp_gt_u32 s44, 13
	s_cbranch_scc0 .LBB0_1097
	s_and_b64 vcc, exec, s[20:21]
	s_cbranch_vccz .LBB0_1100
	s_barrier

.LBB0_1254:
	ds_read_b128 v[130:133], v167
	ds_read_b128 v[134:137], v167 offset:1024
	ds_read_b128 v[156:159], v167 offset:2048
	ds_read_b128 v[160:163], v167 offset:3072
	ds_read_b128 v[170:173], v168
	ds_read_b128 v[174:177], v168 offset:1024
	ds_read_b128 v[178:181], v168 offset:2048
	ds_read_b128 v[182:185], v168 offset:3072
	s_add_u32 s14, s12, 0xfffc0080
	s_addc_u32 s15, s13, -1
	s_cmp_eq_u32 s39, 12
	s_cselect_b32 s17, s9, s15
	s_cselect_b32 s16, s8, s14
	s_cselect_b32 s15, s11, s19
	s_cselect_b32 s14, s10, s7
	v_lshl_add_u64 v[218:219], s[12:13], 0, v[148:149]
	s_add_i32 m0, s51, 0xc000
	ds_read_b128 v[186:189], v169
	ds_read_b128 v[190:193], v169 offset:1024
	ds_read_b128 v[194:197], v169 offset:2048
	ds_read_b128 v[198:201], v169 offset:3072
	ds_read_b128 v[202:205], v169 offset:4096
	ds_read_b128 v[206:209], v169 offset:5120
	ds_read_b128 v[210:213], v169 offset:6144
	ds_read_b128 v[214:217], v169 offset:7168
	global_load_lds_dwordx4 v[218:219], off
	v_lshl_add_u64 v[218:219], s[12:13], 0, v[150:151]
	s_add_i32 m0, s51, 0xe000
	s_nop 0
	global_load_lds_dwordx4 v[218:219], off
	s_waitcnt vmcnt(8)
	s_waitcnt lgkmcnt(0)
	s_barrier
	s_waitcnt lgkmcnt(0)
	v_mfma_f32_16x16x32_bf16 v[126:129], v[130:133], v[186:189], v[126:129]
	v_mfma_f32_16x16x32_bf16 v[122:125], v[156:159], v[186:189], v[122:125]
	v_mfma_f32_16x16x32_bf16 v[118:121], v[130:133], v[194:197], v[118:121]
	v_mfma_f32_16x16x32_bf16 v[114:117], v[156:159], v[194:197], v[114:117]
	v_mfma_f32_16x16x32_bf16 v[110:113], v[130:133], v[202:205], v[110:113]
	v_mfma_f32_16x16x32_bf16 v[106:109], v[156:159], v[202:205], v[106:109]
	v_mfma_f32_16x16x32_bf16 v[102:105], v[130:133], v[210:213], v[102:105]
	v_mfma_f32_16x16x32_bf16 v[98:101], v[156:159], v[210:213], v[98:101]
	v_mfma_f32_16x16x32_bf16 v[126:129], v[134:137], v[190:193], v[126:129]
	v_mfma_f32_16x16x32_bf16 v[122:125], v[160:163], v[190:193], v[122:125]
	v_mfma_f32_16x16x32_bf16 v[118:121], v[134:137], v[198:201], v[118:121]
	v_mfma_f32_16x16x32_bf16 v[114:117], v[160:163], v[198:201], v[114:117]
	v_mfma_f32_16x16x32_bf16 v[110:113], v[134:137], v[206:209], v[110:113]
	v_mfma_f32_16x16x32_bf16 v[106:109], v[160:163], v[206:209], v[106:109]
	v_mfma_f32_16x16x32_bf16 v[102:105], v[134:137], v[214:217], v[102:105]
	v_mfma_f32_16x16x32_bf16 v[98:101], v[160:163], v[214:217], v[98:101]
	v_mfma_f32_16x16x32_bf16 v[62:65], v[170:173], v[186:189], v[62:65]
	v_mfma_f32_16x16x32_bf16 v[58:61], v[178:181], v[186:189], v[58:61]
	v_mfma_f32_16x16x32_bf16 v[54:57], v[170:173], v[194:197], v[54:57]
	v_mfma_f32_16x16x32_bf16 v[50:53], v[178:181], v[194:197], v[50:53]
	v_mfma_f32_16x16x32_bf16 v[46:49], v[170:173], v[202:205], v[46:49]
	v_mfma_f32_16x16x32_bf16 v[42:45], v[178:181], v[202:205], v[42:45]
	v_mfma_f32_16x16x32_bf16 v[38:41], v[170:173], v[210:213], v[38:41]
	v_mfma_f32_16x16x32_bf16 v[34:37], v[178:181], v[210:213], v[34:37]
	v_mfma_f32_16x16x32_bf16 v[62:65], v[174:177], v[190:193], v[62:65]
	v_mfma_f32_16x16x32_bf16 v[58:61], v[182:185], v[190:193], v[58:61]
	v_mfma_f32_16x16x32_bf16 v[54:57], v[174:177], v[198:201], v[54:57]
	v_mfma_f32_16x16x32_bf16 v[50:53], v[182:185], v[198:201], v[50:53]
	v_mfma_f32_16x16x32_bf16 v[46:49], v[174:177], v[206:209], v[46:49]
	v_mfma_f32_16x16x32_bf16 v[42:45], v[182:185], v[206:209], v[42:45]
	v_mfma_f32_16x16x32_bf16 v[38:41], v[174:177], v[214:217], v[38:41]
	v_mfma_f32_16x16x32_bf16 v[34:37], v[182:185], v[214:217], v[34:37]
	s_barrier
	s_add_i32 s41, s74, s50
	v_lshl_add_u64 v[218:219], s[14:15], 0, v[140:141]
	s_mov_b32 m0, s41
	ds_read_b128 v[186:189], v169 offset:16384
	ds_read_b128 v[190:193], v169 offset:17408
	ds_read_b128 v[194:197], v169 offset:18432
	ds_read_b128 v[198:201], v169 offset:19456
	ds_read_b128 v[202:205], v169 offset:20480
	ds_read_b128 v[206:209], v169 offset:21504
	ds_read_b128 v[210:213], v169 offset:22528
	ds_read_b128 v[214:217], v169 offset:23552
	global_load_lds_dwordx4 v[218:219], off
	s_add_i32 m0, s41, 0x2000
	s_add_u32 s44, s14, 0x40000
	v_lshl_add_u64 v[220:221], s[14:15], 0, v[144:145]
	s_addc_u32 s45, s15, 0
	s_add_i32 s41, s75, s50
	global_load_lds_dwordx4 v[220:221], off
	v_lshl_add_u64 v[222:223], s[44:45], 0, v[140:141]
	s_mov_b32 m0, s41
	v_lshl_add_u64 v[224:225], s[16:17], 0, v[142:143]
	global_load_lds_dwordx4 v[222:223], off
	v_lshl_add_u64 v[222:223], s[44:45], 0, v[144:145]
	s_add_i32 m0, s41, 0x2000
	s_nop 0
	global_load_lds_dwordx4 v[222:223], off
	v_lshl_add_u64 v[222:223], s[16:17], 0, v[138:139]
	s_mov_b32 m0, s51
	s_nop 0
	global_load_lds_dwordx4 v[222:223], off
	s_mov_b32 m0, s52
	s_nop 0
	global_load_lds_dwordx4 v[224:225], off
	s_waitcnt vmcnt(8)
	s_waitcnt lgkmcnt(0)
	s_barrier
	s_waitcnt lgkmcnt(0)
	v_mfma_f32_16x16x32_bf16 v[94:97], v[130:133], v[186:189], v[94:97]
	v_mfma_f32_16x16x32_bf16 v[90:93], v[156:159], v[186:189], v[90:93]
	v_mfma_f32_16x16x32_bf16 v[86:89], v[130:133], v[194:197], v[86:89]
	v_mfma_f32_16x16x32_bf16 v[82:85], v[156:159], v[194:197], v[82:85]
	v_mfma_f32_16x16x32_bf16 v[78:81], v[130:133], v[202:205], v[78:81]
	v_mfma_f32_16x16x32_bf16 v[74:77], v[156:159], v[202:205], v[74:77]
	v_mfma_f32_16x16x32_bf16 v[70:73], v[130:133], v[210:213], v[70:73]
	v_mfma_f32_16x16x32_bf16 v[66:69], v[156:159], v[210:213], v[66:69]
	v_mfma_f32_16x16x32_bf16 v[94:97], v[134:137], v[190:193], v[94:97]
	v_mfma_f32_16x16x32_bf16 v[90:93], v[160:163], v[190:193], v[90:93]
	v_mfma_f32_16x16x32_bf16 v[86:89], v[134:137], v[198:201], v[86:89]
	v_mfma_f32_16x16x32_bf16 v[82:85], v[160:163], v[198:201], v[82:85]
	v_mfma_f32_16x16x32_bf16 v[78:81], v[134:137], v[206:209], v[78:81]
	v_mfma_f32_16x16x32_bf16 v[74:77], v[160:163], v[206:209], v[74:77]
	v_mfma_f32_16x16x32_bf16 v[70:73], v[134:137], v[214:217], v[70:73]
	v_mfma_f32_16x16x32_bf16 v[66:69], v[160:163], v[214:217], v[66:69]
	v_mfma_f32_16x16x32_bf16 v[30:33], v[170:173], v[186:189], v[30:33]
	v_mfma_f32_16x16x32_bf16 v[26:29], v[178:181], v[186:189], v[26:29]
	v_mfma_f32_16x16x32_bf16 v[22:25], v[170:173], v[194:197], v[22:25]
	v_mfma_f32_16x16x32_bf16 v[18:21], v[178:181], v[194:197], v[18:21]
	v_mfma_f32_16x16x32_bf16 v[14:17], v[170:173], v[202:205], v[14:17]
	v_mfma_f32_16x16x32_bf16 v[10:13], v[178:181], v[202:205], v[10:13]
	v_mfma_f32_16x16x32_bf16 v[6:9], v[170:173], v[210:213], v[6:9]
	v_mfma_f32_16x16x32_bf16 v[2:5], v[178:181], v[210:213], v[2:5]
	v_mfma_f32_16x16x32_bf16 v[30:33], v[174:177], v[190:193], v[30:33]
	v_mfma_f32_16x16x32_bf16 v[26:29], v[182:185], v[190:193], v[26:29]
	v_mfma_f32_16x16x32_bf16 v[22:25], v[174:177], v[198:201], v[22:25]
	v_mfma_f32_16x16x32_bf16 v[18:21], v[182:185], v[198:201], v[18:21]
	v_mfma_f32_16x16x32_bf16 v[14:17], v[174:177], v[206:209], v[14:17]
	v_mfma_f32_16x16x32_bf16 v[10:13], v[182:185], v[206:209], v[10:13]
	v_mfma_f32_16x16x32_bf16 v[6:9], v[174:177], v[214:217], v[6:9]
	v_mfma_f32_16x16x32_bf16 v[2:5], v[182:185], v[214:217], v[2:5]
	s_barrier
	s_add_i32 s41, 0, 0x18000
	v_add_u32_e32 v146, s41, v165
	s_add_i32 s44, 0, 0x1c000
	ds_read_b128 v[130:133], v146
	ds_read_b128 v[134:137], v146 offset:1024
	ds_read_b128 v[156:159], v146 offset:2048
	ds_read_b128 v[160:163], v146 offset:3072
	v_add_u32_e32 v146, s44, v165
	ds_read_b128 v[170:173], v146
	ds_read_b128 v[174:177], v146 offset:1024
	ds_read_b128 v[178:181], v146 offset:2048
	ds_read_b128 v[182:185], v146 offset:3072
	s_add_u32 s16, s16, 0x40000
	s_addc_u32 s17, s17, 0
	s_mov_b32 m0, s53
	v_lshl_add_u64 v[226:227], s[16:17], 0, v[138:139]
	ds_read_b128 v[186:189], v169 offset:32768
	ds_read_b128 v[190:193], v169 offset:33792
	ds_read_b128 v[194:197], v169 offset:34816
	ds_read_b128 v[198:201], v169 offset:35840
	ds_read_b128 v[202:205], v169 offset:36864
	ds_read_b128 v[206:209], v169 offset:37888
	ds_read_b128 v[210:213], v169 offset:38912
	ds_read_b128 v[214:217], v169 offset:39936
	global_load_lds_dwordx4 v[226:227], off
	v_lshl_add_u64 v[226:227], s[16:17], 0, v[142:143]
	s_mov_b32 m0, s54
	s_nop 0
	global_load_lds_dwordx4 v[226:227], off
	s_waitcnt vmcnt(8)
	s_waitcnt lgkmcnt(0)
	s_barrier
	s_waitcnt lgkmcnt(0)
	v_mfma_f32_16x16x32_bf16 v[126:129], v[130:133], v[186:189], v[126:129]
	v_mfma_f32_16x16x32_bf16 v[122:125], v[156:159], v[186:189], v[122:125]
	v_mfma_f32_16x16x32_bf16 v[118:121], v[130:133], v[194:197], v[118:121]
	v_mfma_f32_16x16x32_bf16 v[114:117], v[156:159], v[194:197], v[114:117]
	v_mfma_f32_16x16x32_bf16 v[110:113], v[130:133], v[202:205], v[110:113]
	v_mfma_f32_16x16x32_bf16 v[106:109], v[156:159], v[202:205], v[106:109]
	v_mfma_f32_16x16x32_bf16 v[102:105], v[130:133], v[210:213], v[102:105]
	v_mfma_f32_16x16x32_bf16 v[98:101], v[156:159], v[210:213], v[98:101]
	v_mfma_f32_16x16x32_bf16 v[126:129], v[134:137], v[190:193], v[126:129]
	v_mfma_f32_16x16x32_bf16 v[122:125], v[160:163], v[190:193], v[122:125]
	v_mfma_f32_16x16x32_bf16 v[118:121], v[134:137], v[198:201], v[118:121]
	v_mfma_f32_16x16x32_bf16 v[114:117], v[160:163], v[198:201], v[114:117]
	v_mfma_f32_16x16x32_bf16 v[110:113], v[134:137], v[206:209], v[110:113]
	v_mfma_f32_16x16x32_bf16 v[106:109], v[160:163], v[206:209], v[106:109]
	v_mfma_f32_16x16x32_bf16 v[102:105], v[134:137], v[214:217], v[102:105]
	v_mfma_f32_16x16x32_bf16 v[98:101], v[160:163], v[214:217], v[98:101]
	v_mfma_f32_16x16x32_bf16 v[62:65], v[170:173], v[186:189], v[62:65]
	v_mfma_f32_16x16x32_bf16 v[58:61], v[178:181], v[186:189], v[58:61]
	v_mfma_f32_16x16x32_bf16 v[54:57], v[170:173], v[194:197], v[54:57]
	v_mfma_f32_16x16x32_bf16 v[50:53], v[178:181], v[194:197], v[50:53]
	v_mfma_f32_16x16x32_bf16 v[46:49], v[170:173], v[202:205], v[46:49]
	v_mfma_f32_16x16x32_bf16 v[42:45], v[178:181], v[202:205], v[42:45]
	v_mfma_f32_16x16x32_bf16 v[38:41], v[170:173], v[210:213], v[38:41]
	v_mfma_f32_16x16x32_bf16 v[34:37], v[178:181], v[210:213], v[34:37]
	v_mfma_f32_16x16x32_bf16 v[62:65], v[174:177], v[190:193], v[62:65]
	v_mfma_f32_16x16x32_bf16 v[58:61], v[182:185], v[190:193], v[58:61]
	v_mfma_f32_16x16x32_bf16 v[54:57], v[174:177], v[198:201], v[54:57]
	v_mfma_f32_16x16x32_bf16 v[50:53], v[182:185], v[198:201], v[50:53]
	v_mfma_f32_16x16x32_bf16 v[46:49], v[174:177], v[206:209], v[46:49]
	v_mfma_f32_16x16x32_bf16 v[42:45], v[182:185], v[206:209], v[42:45]
	v_mfma_f32_16x16x32_bf16 v[38:41], v[174:177], v[214:217], v[38:41]
	v_mfma_f32_16x16x32_bf16 v[34:37], v[182:185], v[214:217], v[34:37]
	s_barrier
	s_add_i32 s16, s41, s50
	v_lshl_add_u64 v[218:219], v[218:219], 0, s[30:31]
	s_mov_b32 m0, s16
	ds_read_b128 v[186:189], v169 offset:49152
	ds_read_b128 v[190:193], v169 offset:50176
	ds_read_b128 v[194:197], v169 offset:51200
	ds_read_b128 v[198:201], v169 offset:52224
	ds_read_b128 v[202:205], v169 offset:53248
	ds_read_b128 v[206:209], v169 offset:54272
	ds_read_b128 v[210:213], v169 offset:55296
	ds_read_b128 v[214:217], v169 offset:56320
	global_load_lds_dwordx4 v[218:219], off
	s_add_i32 m0, s16, 0x2000
	s_add_u32 s14, s14, 0x40080
	v_lshl_add_u64 v[218:219], v[220:221], 0, s[30:31]
	s_addc_u32 s15, s15, 0
	s_add_i32 s16, s44, s50
	global_load_lds_dwordx4 v[218:219], off
	v_lshl_add_u64 v[218:219], s[14:15], 0, v[140:141]
	s_mov_b32 m0, s16
	s_nop 0
	global_load_lds_dwordx4 v[218:219], off
	v_lshl_add_u64 v[218:219], s[14:15], 0, v[144:145]
	s_add_i32 m0, s16, 0x2000
	s_nop 0
	global_load_lds_dwordx4 v[218:219], off
	v_lshl_add_u64 v[218:219], v[222:223], 0, s[30:31]
	s_mov_b32 m0, s61
	s_nop 0
	global_load_lds_dwordx4 v[218:219], off
	v_lshl_add_u64 v[218:219], v[224:225], 0, s[30:31]
	s_mov_b32 m0, s62
	s_nop 0
	global_load_lds_dwordx4 v[218:219], off
	s_waitcnt vmcnt(8)
	s_waitcnt lgkmcnt(0)
	s_barrier
	s_waitcnt lgkmcnt(0)
	v_mfma_f32_16x16x32_bf16 v[94:97], v[130:133], v[186:189], v[94:97]
	v_mfma_f32_16x16x32_bf16 v[90:93], v[156:159], v[186:189], v[90:93]
	v_mfma_f32_16x16x32_bf16 v[86:89], v[130:133], v[194:197], v[86:89]
	v_mfma_f32_16x16x32_bf16 v[82:85], v[156:159], v[194:197], v[82:85]
	v_mfma_f32_16x16x32_bf16 v[78:81], v[130:133], v[202:205], v[78:81]
	v_mfma_f32_16x16x32_bf16 v[74:77], v[156:159], v[202:205], v[74:77]
	v_mfma_f32_16x16x32_bf16 v[70:73], v[130:133], v[210:213], v[70:73]
	v_mfma_f32_16x16x32_bf16 v[66:69], v[156:159], v[210:213], v[66:69]
	v_mfma_f32_16x16x32_bf16 v[94:97], v[134:137], v[190:193], v[94:97]
	v_mfma_f32_16x16x32_bf16 v[90:93], v[160:163], v[190:193], v[90:93]
	v_mfma_f32_16x16x32_bf16 v[86:89], v[134:137], v[198:201], v[86:89]
	v_mfma_f32_16x16x32_bf16 v[82:85], v[160:163], v[198:201], v[82:85]
	v_mfma_f32_16x16x32_bf16 v[78:81], v[134:137], v[206:209], v[78:81]
	v_mfma_f32_16x16x32_bf16 v[74:77], v[160:163], v[206:209], v[74:77]
	v_mfma_f32_16x16x32_bf16 v[70:73], v[134:137], v[214:217], v[70:73]
	v_mfma_f32_16x16x32_bf16 v[66:69], v[160:163], v[214:217], v[66:69]
	v_mfma_f32_16x16x32_bf16 v[30:33], v[170:173], v[186:189], v[30:33]
	v_mfma_f32_16x16x32_bf16 v[26:29], v[178:181], v[186:189], v[26:29]
	v_mfma_f32_16x16x32_bf16 v[22:25], v[170:173], v[194:197], v[22:25]
	v_mfma_f32_16x16x32_bf16 v[18:21], v[178:181], v[194:197], v[18:21]
	v_mfma_f32_16x16x32_bf16 v[14:17], v[170:173], v[202:205], v[14:17]
	v_mfma_f32_16x16x32_bf16 v[10:13], v[178:181], v[202:205], v[10:13]
	v_mfma_f32_16x16x32_bf16 v[6:9], v[170:173], v[210:213], v[6:9]
	v_mfma_f32_16x16x32_bf16 v[2:5], v[178:181], v[210:213], v[2:5]
	v_mfma_f32_16x16x32_bf16 v[30:33], v[174:177], v[190:193], v[30:33]
	v_mfma_f32_16x16x32_bf16 v[26:29], v[182:185], v[190:193], v[26:29]
	v_mfma_f32_16x16x32_bf16 v[22:25], v[174:177], v[198:201], v[22:25]
	v_mfma_f32_16x16x32_bf16 v[18:21], v[182:185], v[198:201], v[18:21]
	v_mfma_f32_16x16x32_bf16 v[14:17], v[174:177], v[206:209], v[14:17]
	v_mfma_f32_16x16x32_bf16 v[10:13], v[182:185], v[206:209], v[10:13]
	v_mfma_f32_16x16x32_bf16 v[6:9], v[174:177], v[214:217], v[6:9]
	v_mfma_f32_16x16x32_bf16 v[2:5], v[182:185], v[214:217], v[2:5]
	s_barrier
	s_add_i32 s39, s39, 2
	s_add_u32 s12, s12, 0x100
	s_addc_u32 s13, s13, 0
	s_add_u32 s7, s7, 0x100
	s_addc_u32 s19, s19, 0
	s_cmp_gt_u32 s39, 13
	s_cbranch_scc0 .LBB0_1254
	s_and_b64 vcc, exec, s[34:35]
	s_cbranch_vccz .LBB0_1257
	s_barrier

.LBB0_1449:
	ds_read_b128 v[154:157], v151
	ds_read_b128 v[158:161], v151 offset:1024
	ds_read_b128 v[162:165], v151 offset:2048
	ds_read_b128 v[166:169], v151 offset:3072
	ds_read_b128 v[170:173], v152
	ds_read_b128 v[174:177], v152 offset:1024
	ds_read_b128 v[178:181], v152 offset:2048
	ds_read_b128 v[182:185], v152 offset:3072
	s_add_u32 s34, s30, 0xfffc0080
	s_addc_u32 s35, s31, -1
	s_cmp_eq_u32 s45, 12
	s_cselect_b32 s37, s27, s35
	s_cselect_b32 s36, s26, s34
	s_cselect_b32 s35, s29, s19
	s_cselect_b32 s34, s28, s17
	v_lshl_add_u64 v[220:221], s[30:31], 0, v[138:139]
	s_add_i32 m0, s25, 0xc000
	ds_read_b128 v[186:189], v153
	ds_read_b128 v[190:193], v153 offset:1024
	ds_read_b128 v[194:197], v153 offset:2048
	ds_read_b128 v[198:201], v153 offset:3072
	ds_read_b128 v[202:205], v153 offset:4096
	ds_read_b128 v[208:211], v153 offset:5120
	ds_read_b128 v[212:215], v153 offset:6144
	ds_read_b128 v[216:219], v153 offset:7168
	global_load_lds_dwordx4 v[220:221], off
	v_lshl_add_u64 v[220:221], s[30:31], 0, v[140:141]
	s_add_i32 m0, s25, 0xe000
	s_nop 0
	global_load_lds_dwordx4 v[220:221], off
	s_waitcnt vmcnt(8)
	s_waitcnt lgkmcnt(0)
	s_barrier
	s_waitcnt lgkmcnt(0)
	v_mfma_f32_16x16x32_bf16 v[126:129], v[154:157], v[186:189], v[126:129]
	v_mfma_f32_16x16x32_bf16 v[122:125], v[162:165], v[186:189], v[122:125]
	v_mfma_f32_16x16x32_bf16 v[110:113], v[154:157], v[194:197], v[110:113]
	v_mfma_f32_16x16x32_bf16 v[106:109], v[162:165], v[194:197], v[106:109]
	v_mfma_f32_16x16x32_bf16 v[94:97], v[154:157], v[202:205], v[94:97]
	v_mfma_f32_16x16x32_bf16 v[90:93], v[162:165], v[202:205], v[90:93]
	v_mfma_f32_16x16x32_bf16 v[78:81], v[154:157], v[212:215], v[78:81]
	v_mfma_f32_16x16x32_bf16 v[74:77], v[162:165], v[212:215], v[74:77]
	v_mfma_f32_16x16x32_bf16 v[126:129], v[158:161], v[190:193], v[126:129]
	v_mfma_f32_16x16x32_bf16 v[122:125], v[166:169], v[190:193], v[122:125]
	v_mfma_f32_16x16x32_bf16 v[110:113], v[158:161], v[198:201], v[110:113]
	v_mfma_f32_16x16x32_bf16 v[106:109], v[166:169], v[198:201], v[106:109]
	v_mfma_f32_16x16x32_bf16 v[94:97], v[158:161], v[208:211], v[94:97]
	v_mfma_f32_16x16x32_bf16 v[90:93], v[166:169], v[208:211], v[90:93]
	v_mfma_f32_16x16x32_bf16 v[78:81], v[158:161], v[216:219], v[78:81]
	v_mfma_f32_16x16x32_bf16 v[74:77], v[166:169], v[216:219], v[74:77]
	v_mfma_f32_16x16x32_bf16 v[118:121], v[170:173], v[186:189], v[118:121]
	v_mfma_f32_16x16x32_bf16 v[114:117], v[178:181], v[186:189], v[114:117]
	v_mfma_f32_16x16x32_bf16 v[102:105], v[170:173], v[194:197], v[102:105]
	v_mfma_f32_16x16x32_bf16 v[98:101], v[178:181], v[194:197], v[98:101]
	v_mfma_f32_16x16x32_bf16 v[86:89], v[170:173], v[202:205], v[86:89]
	v_mfma_f32_16x16x32_bf16 v[82:85], v[178:181], v[202:205], v[82:85]
	v_mfma_f32_16x16x32_bf16 v[70:73], v[170:173], v[212:215], v[70:73]
	v_mfma_f32_16x16x32_bf16 v[66:69], v[178:181], v[212:215], v[66:69]
	v_mfma_f32_16x16x32_bf16 v[118:121], v[174:177], v[190:193], v[118:121]
	v_mfma_f32_16x16x32_bf16 v[114:117], v[182:185], v[190:193], v[114:117]
	v_mfma_f32_16x16x32_bf16 v[102:105], v[174:177], v[198:201], v[102:105]
	v_mfma_f32_16x16x32_bf16 v[98:101], v[182:185], v[198:201], v[98:101]
	v_mfma_f32_16x16x32_bf16 v[86:89], v[174:177], v[208:211], v[86:89]
	v_mfma_f32_16x16x32_bf16 v[82:85], v[182:185], v[208:211], v[82:85]
	v_mfma_f32_16x16x32_bf16 v[70:73], v[174:177], v[216:219], v[70:73]
	v_mfma_f32_16x16x32_bf16 v[66:69], v[182:185], v[216:219], v[66:69]
	s_barrier
	s_add_i32 s57, s54, s41
	v_lshl_add_u64 v[220:221], s[34:35], 0, v[132:133]
	s_mov_b32 m0, s57
	ds_read_b128 v[186:189], v153 offset:16384
	ds_read_b128 v[190:193], v153 offset:17408
	ds_read_b128 v[194:197], v153 offset:18432
	ds_read_b128 v[198:201], v153 offset:19456
	ds_read_b128 v[202:205], v153 offset:20480
	ds_read_b128 v[208:211], v153 offset:21504
	ds_read_b128 v[212:215], v153 offset:22528
	ds_read_b128 v[216:219], v153 offset:23552
	global_load_lds_dwordx4 v[220:221], off
	s_add_i32 m0, s57, 0x2000
	s_add_u32 s58, s34, 0x580000
	v_lshl_add_u64 v[222:223], s[34:35], 0, v[136:137]
	s_addc_u32 s59, s35, 0
	s_add_i32 s57, s55, s41
	global_load_lds_dwordx4 v[222:223], off
	v_lshl_add_u64 v[224:225], s[58:59], 0, v[132:133]
	s_mov_b32 m0, s57
	v_lshl_add_u64 v[226:227], s[36:37], 0, v[134:135]
	global_load_lds_dwordx4 v[224:225], off
	v_lshl_add_u64 v[224:225], s[58:59], 0, v[136:137]
	s_add_i32 m0, s57, 0x2000
	s_nop 0
	global_load_lds_dwordx4 v[224:225], off
	v_lshl_add_u64 v[224:225], s[36:37], 0, v[130:131]
	s_mov_b32 m0, s25
	s_nop 0
	global_load_lds_dwordx4 v[224:225], off
	s_mov_b32 m0, s46
	s_nop 0
	global_load_lds_dwordx4 v[226:227], off
	s_waitcnt vmcnt(8)
	s_waitcnt lgkmcnt(0)
	s_barrier
	s_waitcnt lgkmcnt(0)
	v_mfma_f32_16x16x32_bf16 v[62:65], v[154:157], v[186:189], v[62:65]
	v_mfma_f32_16x16x32_bf16 v[58:61], v[162:165], v[186:189], v[58:61]
	v_mfma_f32_16x16x32_bf16 v[46:49], v[154:157], v[194:197], v[46:49]
	v_mfma_f32_16x16x32_bf16 v[42:45], v[162:165], v[194:197], v[42:45]
	v_mfma_f32_16x16x32_bf16 v[30:33], v[154:157], v[202:205], v[30:33]
	v_mfma_f32_16x16x32_bf16 v[26:29], v[162:165], v[202:205], v[26:29]
	v_mfma_f32_16x16x32_bf16 v[14:17], v[154:157], v[212:215], v[14:17]
	v_mfma_f32_16x16x32_bf16 v[10:13], v[162:165], v[212:215], v[10:13]
	v_mfma_f32_16x16x32_bf16 v[62:65], v[158:161], v[190:193], v[62:65]
	v_mfma_f32_16x16x32_bf16 v[58:61], v[166:169], v[190:193], v[58:61]
	v_mfma_f32_16x16x32_bf16 v[46:49], v[158:161], v[198:201], v[46:49]
	v_mfma_f32_16x16x32_bf16 v[42:45], v[166:169], v[198:201], v[42:45]
	v_mfma_f32_16x16x32_bf16 v[30:33], v[158:161], v[208:211], v[30:33]
	v_mfma_f32_16x16x32_bf16 v[26:29], v[166:169], v[208:211], v[26:29]
	v_mfma_f32_16x16x32_bf16 v[14:17], v[158:161], v[216:219], v[14:17]
	v_mfma_f32_16x16x32_bf16 v[10:13], v[166:169], v[216:219], v[10:13]
	v_mfma_f32_16x16x32_bf16 v[54:57], v[170:173], v[186:189], v[54:57]
	v_mfma_f32_16x16x32_bf16 v[50:53], v[178:181], v[186:189], v[50:53]
	v_mfma_f32_16x16x32_bf16 v[38:41], v[170:173], v[194:197], v[38:41]
	v_mfma_f32_16x16x32_bf16 v[34:37], v[178:181], v[194:197], v[34:37]
	v_mfma_f32_16x16x32_bf16 v[22:25], v[170:173], v[202:205], v[22:25]
	v_mfma_f32_16x16x32_bf16 v[18:21], v[178:181], v[202:205], v[18:21]
	v_mfma_f32_16x16x32_bf16 v[6:9], v[170:173], v[212:215], v[6:9]
	v_mfma_f32_16x16x32_bf16 v[2:5], v[178:181], v[212:215], v[2:5]
	v_mfma_f32_16x16x32_bf16 v[54:57], v[174:177], v[190:193], v[54:57]
	v_mfma_f32_16x16x32_bf16 v[50:53], v[182:185], v[190:193], v[50:53]
	v_mfma_f32_16x16x32_bf16 v[38:41], v[174:177], v[198:201], v[38:41]
	v_mfma_f32_16x16x32_bf16 v[34:37], v[182:185], v[198:201], v[34:37]
	v_mfma_f32_16x16x32_bf16 v[22:25], v[174:177], v[208:211], v[22:25]
	v_mfma_f32_16x16x32_bf16 v[18:21], v[182:185], v[208:211], v[18:21]
	v_mfma_f32_16x16x32_bf16 v[6:9], v[174:177], v[216:219], v[6:9]
	v_mfma_f32_16x16x32_bf16 v[2:5], v[182:185], v[216:219], v[2:5]
	s_barrier
	s_add_i32 s57, 0, 0x18000
	s_add_i32 s58, 0, 0x1c000
	v_add_u32_e32 v166, s57, v149
	v_add_u32_e32 v182, s58, v149
	ds_read_b128 v[154:157], v166
	ds_read_b128 v[158:161], v166 offset:1024
	ds_read_b128 v[162:165], v166 offset:2048
	ds_read_b128 v[166:169], v166 offset:3072
	ds_read_b128 v[170:173], v182
	ds_read_b128 v[174:177], v182 offset:1024
	ds_read_b128 v[178:181], v182 offset:2048
	ds_read_b128 v[182:185], v182 offset:3072
	s_add_u32 s36, s36, 0x40000
	s_addc_u32 s37, s37, 0
	s_mov_b32 m0, s47
	v_lshl_add_u64 v[228:229], s[36:37], 0, v[130:131]
	ds_read_b128 v[186:189], v153 offset:32768
	ds_read_b128 v[190:193], v153 offset:33792
	ds_read_b128 v[194:197], v153 offset:34816
	ds_read_b128 v[198:201], v153 offset:35840
	ds_read_b128 v[202:205], v153 offset:36864
	ds_read_b128 v[208:211], v153 offset:37888
	ds_read_b128 v[212:215], v153 offset:38912
	ds_read_b128 v[216:219], v153 offset:39936
	global_load_lds_dwordx4 v[228:229], off
	v_lshl_add_u64 v[228:229], s[36:37], 0, v[134:135]
	s_mov_b32 m0, s48
	s_nop 0
	global_load_lds_dwordx4 v[228:229], off
	s_waitcnt vmcnt(8)
	s_waitcnt lgkmcnt(0)
	s_barrier
	s_waitcnt lgkmcnt(0)
	v_mfma_f32_16x16x32_bf16 v[126:129], v[154:157], v[186:189], v[126:129]
	v_mfma_f32_16x16x32_bf16 v[122:125], v[162:165], v[186:189], v[122:125]
	v_mfma_f32_16x16x32_bf16 v[110:113], v[154:157], v[194:197], v[110:113]
	v_mfma_f32_16x16x32_bf16 v[106:109], v[162:165], v[194:197], v[106:109]
	v_mfma_f32_16x16x32_bf16 v[94:97], v[154:157], v[202:205], v[94:97]
	v_mfma_f32_16x16x32_bf16 v[90:93], v[162:165], v[202:205], v[90:93]
	v_mfma_f32_16x16x32_bf16 v[78:81], v[154:157], v[212:215], v[78:81]
	v_mfma_f32_16x16x32_bf16 v[74:77], v[162:165], v[212:215], v[74:77]
	v_mfma_f32_16x16x32_bf16 v[126:129], v[158:161], v[190:193], v[126:129]
	v_mfma_f32_16x16x32_bf16 v[122:125], v[166:169], v[190:193], v[122:125]
	v_mfma_f32_16x16x32_bf16 v[110:113], v[158:161], v[198:201], v[110:113]
	v_mfma_f32_16x16x32_bf16 v[106:109], v[166:169], v[198:201], v[106:109]
	v_mfma_f32_16x16x32_bf16 v[94:97], v[158:161], v[208:211], v[94:97]
	v_mfma_f32_16x16x32_bf16 v[90:93], v[166:169], v[208:211], v[90:93]
	v_mfma_f32_16x16x32_bf16 v[78:81], v[158:161], v[216:219], v[78:81]
	v_mfma_f32_16x16x32_bf16 v[74:77], v[166:169], v[216:219], v[74:77]
	v_mfma_f32_16x16x32_bf16 v[118:121], v[170:173], v[186:189], v[118:121]
	v_mfma_f32_16x16x32_bf16 v[114:117], v[178:181], v[186:189], v[114:117]
	v_mfma_f32_16x16x32_bf16 v[102:105], v[170:173], v[194:197], v[102:105]
	v_mfma_f32_16x16x32_bf16 v[98:101], v[178:181], v[194:197], v[98:101]
	v_mfma_f32_16x16x32_bf16 v[86:89], v[170:173], v[202:205], v[86:89]
	v_mfma_f32_16x16x32_bf16 v[82:85], v[178:181], v[202:205], v[82:85]
	v_mfma_f32_16x16x32_bf16 v[70:73], v[170:173], v[212:215], v[70:73]
	v_mfma_f32_16x16x32_bf16 v[66:69], v[178:181], v[212:215], v[66:69]
	v_mfma_f32_16x16x32_bf16 v[118:121], v[174:177], v[190:193], v[118:121]
	v_mfma_f32_16x16x32_bf16 v[114:117], v[182:185], v[190:193], v[114:117]
	v_mfma_f32_16x16x32_bf16 v[102:105], v[174:177], v[198:201], v[102:105]
	v_mfma_f32_16x16x32_bf16 v[98:101], v[182:185], v[198:201], v[98:101]
	v_mfma_f32_16x16x32_bf16 v[86:89], v[174:177], v[208:211], v[86:89]
	v_mfma_f32_16x16x32_bf16 v[82:85], v[182:185], v[208:211], v[82:85]
	v_mfma_f32_16x16x32_bf16 v[70:73], v[174:177], v[216:219], v[70:73]
	v_mfma_f32_16x16x32_bf16 v[66:69], v[182:185], v[216:219], v[66:69]
	s_barrier
	s_add_i32 s36, s57, s41
	v_lshl_add_u64 v[220:221], v[220:221], 0, s[12:13]
	s_mov_b32 m0, s36
	ds_read_b128 v[186:189], v153 offset:49152
	ds_read_b128 v[190:193], v153 offset:50176
	ds_read_b128 v[194:197], v153 offset:51200
	ds_read_b128 v[198:201], v153 offset:52224
	ds_read_b128 v[202:205], v153 offset:53248
	ds_read_b128 v[208:211], v153 offset:54272
	ds_read_b128 v[212:215], v153 offset:55296
	ds_read_b128 v[216:219], v153 offset:56320
	global_load_lds_dwordx4 v[220:221], off
	s_add_i32 m0, s36, 0x2000
	s_add_u32 s34, s34, 0x580080
	v_lshl_add_u64 v[220:221], v[222:223], 0, s[12:13]
	s_addc_u32 s35, s35, 0
	s_add_i32 s36, s58, s41
	global_load_lds_dwordx4 v[220:221], off
	v_lshl_add_u64 v[220:221], s[34:35], 0, v[132:133]
	s_mov_b32 m0, s36
	s_nop 0
	global_load_lds_dwordx4 v[220:221], off
	v_lshl_add_u64 v[220:221], s[34:35], 0, v[136:137]
	s_add_i32 m0, s36, 0x2000
	s_nop 0
	global_load_lds_dwordx4 v[220:221], off
	v_lshl_add_u64 v[220:221], v[224:225], 0, s[12:13]
	s_mov_b32 m0, s51
	s_nop 0
	global_load_lds_dwordx4 v[220:221], off
	v_lshl_add_u64 v[220:221], v[226:227], 0, s[12:13]
	s_mov_b32 m0, s52
	s_nop 0
	global_load_lds_dwordx4 v[220:221], off
	s_waitcnt vmcnt(8)
	s_waitcnt lgkmcnt(0)
	s_barrier
	s_waitcnt lgkmcnt(0)
	v_mfma_f32_16x16x32_bf16 v[62:65], v[154:157], v[186:189], v[62:65]
	v_mfma_f32_16x16x32_bf16 v[58:61], v[162:165], v[186:189], v[58:61]
	v_mfma_f32_16x16x32_bf16 v[46:49], v[154:157], v[194:197], v[46:49]
	v_mfma_f32_16x16x32_bf16 v[42:45], v[162:165], v[194:197], v[42:45]
	v_mfma_f32_16x16x32_bf16 v[30:33], v[154:157], v[202:205], v[30:33]
	v_mfma_f32_16x16x32_bf16 v[26:29], v[162:165], v[202:205], v[26:29]
	v_mfma_f32_16x16x32_bf16 v[14:17], v[154:157], v[212:215], v[14:17]
	v_mfma_f32_16x16x32_bf16 v[10:13], v[162:165], v[212:215], v[10:13]
	v_mfma_f32_16x16x32_bf16 v[62:65], v[158:161], v[190:193], v[62:65]
	v_mfma_f32_16x16x32_bf16 v[58:61], v[166:169], v[190:193], v[58:61]
	v_mfma_f32_16x16x32_bf16 v[46:49], v[158:161], v[198:201], v[46:49]
	v_mfma_f32_16x16x32_bf16 v[42:45], v[166:169], v[198:201], v[42:45]
	v_mfma_f32_16x16x32_bf16 v[30:33], v[158:161], v[208:211], v[30:33]
	v_mfma_f32_16x16x32_bf16 v[26:29], v[166:169], v[208:211], v[26:29]
	v_mfma_f32_16x16x32_bf16 v[14:17], v[158:161], v[216:219], v[14:17]
	v_mfma_f32_16x16x32_bf16 v[10:13], v[166:169], v[216:219], v[10:13]
	v_mfma_f32_16x16x32_bf16 v[54:57], v[170:173], v[186:189], v[54:57]
	v_mfma_f32_16x16x32_bf16 v[50:53], v[178:181], v[186:189], v[50:53]
	v_mfma_f32_16x16x32_bf16 v[38:41], v[170:173], v[194:197], v[38:41]
	v_mfma_f32_16x16x32_bf16 v[34:37], v[178:181], v[194:197], v[34:37]
	v_mfma_f32_16x16x32_bf16 v[22:25], v[170:173], v[202:205], v[22:25]
	v_mfma_f32_16x16x32_bf16 v[18:21], v[178:181], v[202:205], v[18:21]
	v_mfma_f32_16x16x32_bf16 v[6:9], v[170:173], v[212:215], v[6:9]
	v_mfma_f32_16x16x32_bf16 v[2:5], v[178:181], v[212:215], v[2:5]
	v_mfma_f32_16x16x32_bf16 v[54:57], v[174:177], v[190:193], v[54:57]
	v_mfma_f32_16x16x32_bf16 v[50:53], v[182:185], v[190:193], v[50:53]
	v_mfma_f32_16x16x32_bf16 v[38:41], v[174:177], v[198:201], v[38:41]
	v_mfma_f32_16x16x32_bf16 v[34:37], v[182:185], v[198:201], v[34:37]
	v_mfma_f32_16x16x32_bf16 v[22:25], v[174:177], v[208:211], v[22:25]
	v_mfma_f32_16x16x32_bf16 v[18:21], v[182:185], v[208:211], v[18:21]
	v_mfma_f32_16x16x32_bf16 v[6:9], v[174:177], v[216:219], v[6:9]
	v_mfma_f32_16x16x32_bf16 v[2:5], v[182:185], v[216:219], v[2:5]
	s_barrier
	s_add_i32 s45, s45, 2
	s_add_u32 s30, s30, 0x100
	s_addc_u32 s31, s31, 0
	s_add_u32 s17, s17, 0x100
	s_addc_u32 s19, s19, 0
	s_cmp_gt_u32 s45, 13
	s_cbranch_scc0 .LBB0_1449
	s_and_b64 vcc, exec, s[14:15]
	s_cbranch_vccz .LBB0_1452
	s_barrier

.LBB0_1541:
	ds_read_b128 v[130:133], v210
	ds_read_b128 v[134:137], v210 offset:1024
	ds_read_b128 v[138:141], v210 offset:2048
	ds_read_b128 v[142:145], v210 offset:3072
	ds_read_b128 v[146:149], v211
	ds_read_b128 v[150:153], v211 offset:1024
	ds_read_b128 v[154:157], v211 offset:2048
	ds_read_b128 v[158:161], v211 offset:3072
	s_add_u32 s40, s38, 0xfff50080
	s_addc_u32 s41, s39, -1
	s_cmp_eq_u32 s77, 40
	s_cselect_b32 s43, s35, s41
	s_cselect_b32 s42, s34, s40
	s_cselect_b32 s41, s37, s45
	s_cselect_b32 s40, s36, s44
	v_lshl_add_u64 v[218:219], s[38:39], 0, v[178:179]
	s_add_i32 m0, s50, 0xc000
	ds_read_b128 v[162:165], v212
	ds_read_b128 v[166:169], v212 offset:1024
	ds_read_b128 v[186:189], v212 offset:2048
	ds_read_b128 v[190:193], v212 offset:3072
	ds_read_b128 v[194:197], v212 offset:4096
	ds_read_b128 v[198:201], v212 offset:5120
	ds_read_b128 v[202:205], v212 offset:6144
	ds_read_b128 v[214:217], v212 offset:7168
	global_load_lds_dwordx4 v[218:219], off
	v_lshl_add_u64 v[218:219], s[38:39], 0, v[180:181]
	s_add_i32 m0, s50, 0xe000
	s_nop 0
	global_load_lds_dwordx4 v[218:219], off
	s_waitcnt vmcnt(8)
	s_waitcnt lgkmcnt(0)
	s_barrier
	s_waitcnt lgkmcnt(0)
	v_mfma_f32_16x16x32_bf16 v[126:129], v[130:133], v[162:165], v[126:129]
	v_mfma_f32_16x16x32_bf16 v[122:125], v[138:141], v[162:165], v[122:125]
	v_mfma_f32_16x16x32_bf16 v[118:121], v[130:133], v[186:189], v[118:121]
	v_mfma_f32_16x16x32_bf16 v[114:117], v[138:141], v[186:189], v[114:117]
	v_mfma_f32_16x16x32_bf16 v[110:113], v[130:133], v[194:197], v[110:113]
	v_mfma_f32_16x16x32_bf16 v[106:109], v[138:141], v[194:197], v[106:109]
	v_mfma_f32_16x16x32_bf16 v[102:105], v[130:133], v[202:205], v[102:105]
	v_mfma_f32_16x16x32_bf16 v[98:101], v[138:141], v[202:205], v[98:101]
	v_mfma_f32_16x16x32_bf16 v[126:129], v[134:137], v[166:169], v[126:129]
	v_mfma_f32_16x16x32_bf16 v[122:125], v[142:145], v[166:169], v[122:125]
	v_mfma_f32_16x16x32_bf16 v[118:121], v[134:137], v[190:193], v[118:121]
	v_mfma_f32_16x16x32_bf16 v[114:117], v[142:145], v[190:193], v[114:117]
	v_mfma_f32_16x16x32_bf16 v[110:113], v[134:137], v[198:201], v[110:113]
	v_mfma_f32_16x16x32_bf16 v[106:109], v[142:145], v[198:201], v[106:109]
	v_mfma_f32_16x16x32_bf16 v[102:105], v[134:137], v[214:217], v[102:105]
	v_mfma_f32_16x16x32_bf16 v[98:101], v[142:145], v[214:217], v[98:101]
	v_mfma_f32_16x16x32_bf16 v[70:73], v[146:149], v[162:165], v[70:73]
	v_mfma_f32_16x16x32_bf16 v[66:69], v[154:157], v[162:165], v[66:69]
	v_mfma_f32_16x16x32_bf16 v[62:65], v[146:149], v[186:189], v[62:65]
	v_mfma_f32_16x16x32_bf16 v[54:57], v[154:157], v[186:189], v[54:57]
	v_mfma_f32_16x16x32_bf16 v[46:49], v[146:149], v[194:197], v[46:49]
	v_mfma_f32_16x16x32_bf16 v[42:45], v[154:157], v[194:197], v[42:45]
	v_mfma_f32_16x16x32_bf16 v[38:41], v[146:149], v[202:205], v[38:41]
	v_mfma_f32_16x16x32_bf16 v[34:37], v[154:157], v[202:205], v[34:37]
	v_mfma_f32_16x16x32_bf16 v[70:73], v[150:153], v[166:169], v[70:73]
	v_mfma_f32_16x16x32_bf16 v[66:69], v[158:161], v[166:169], v[66:69]
	v_mfma_f32_16x16x32_bf16 v[62:65], v[150:153], v[190:193], v[62:65]
	v_mfma_f32_16x16x32_bf16 v[54:57], v[158:161], v[190:193], v[54:57]
	v_mfma_f32_16x16x32_bf16 v[46:49], v[150:153], v[198:201], v[46:49]
	v_mfma_f32_16x16x32_bf16 v[42:45], v[158:161], v[198:201], v[42:45]
	v_mfma_f32_16x16x32_bf16 v[38:41], v[150:153], v[214:217], v[38:41]
	v_mfma_f32_16x16x32_bf16 v[34:37], v[158:161], v[214:217], v[34:37]
	s_barrier
	s_add_i32 s78, s61, s48
	v_lshl_add_u64 v[218:219], s[40:41], 0, v[172:173]
	s_mov_b32 m0, s78
	ds_read_b128 v[162:165], v212 offset:16384
	ds_read_b128 v[166:169], v212 offset:17408
	ds_read_b128 v[186:189], v212 offset:18432
	ds_read_b128 v[190:193], v212 offset:19456
	ds_read_b128 v[194:197], v212 offset:20480
	ds_read_b128 v[198:201], v212 offset:21504
	ds_read_b128 v[202:205], v212 offset:22528
	ds_read_b128 v[214:217], v212 offset:23552
	global_load_lds_dwordx4 v[218:219], off
	s_add_i32 m0, s78, 0x2000
	s_add_u32 s78, s40, 0xb0000
	v_lshl_add_u64 v[220:221], s[40:41], 0, v[176:177]
	s_addc_u32 s79, s41, 0
	s_add_i32 s80, s62, s48
	global_load_lds_dwordx4 v[220:221], off
	v_lshl_add_u64 v[222:223], s[78:79], 0, v[172:173]
	s_mov_b32 m0, s80
	v_lshl_add_u64 v[224:225], s[42:43], 0, v[174:175]
	global_load_lds_dwordx4 v[222:223], off
	v_lshl_add_u64 v[222:223], s[78:79], 0, v[176:177]
	s_add_i32 m0, s80, 0x2000
	s_nop 0
	global_load_lds_dwordx4 v[222:223], off
	v_lshl_add_u64 v[222:223], s[42:43], 0, v[170:171]
	s_mov_b32 m0, s50
	s_nop 0
	global_load_lds_dwordx4 v[222:223], off
	s_mov_b32 m0, s51
	s_nop 0
	global_load_lds_dwordx4 v[224:225], off
	s_waitcnt vmcnt(8)
	s_waitcnt lgkmcnt(0)
	s_barrier
	s_waitcnt lgkmcnt(0)
	v_mfma_f32_16x16x32_bf16 v[94:97], v[130:133], v[162:165], v[94:97]
	v_mfma_f32_16x16x32_bf16 v[90:93], v[138:141], v[162:165], v[90:93]
	v_mfma_f32_16x16x32_bf16 v[86:89], v[130:133], v[186:189], v[86:89]
	v_mfma_f32_16x16x32_bf16 v[82:85], v[138:141], v[186:189], v[82:85]
	v_mfma_f32_16x16x32_bf16 v[78:81], v[130:133], v[194:197], v[78:81]
	v_mfma_f32_16x16x32_bf16 v[74:77], v[138:141], v[194:197], v[74:77]
	v_mfma_f32_16x16x32_bf16 v[58:61], v[130:133], v[202:205], v[58:61]
	v_mfma_f32_16x16x32_bf16 v[50:53], v[138:141], v[202:205], v[50:53]
	v_mfma_f32_16x16x32_bf16 v[94:97], v[134:137], v[166:169], v[94:97]
	v_mfma_f32_16x16x32_bf16 v[90:93], v[142:145], v[166:169], v[90:93]
	v_mfma_f32_16x16x32_bf16 v[86:89], v[134:137], v[190:193], v[86:89]
	v_mfma_f32_16x16x32_bf16 v[82:85], v[142:145], v[190:193], v[82:85]
	v_mfma_f32_16x16x32_bf16 v[78:81], v[134:137], v[198:201], v[78:81]
	v_mfma_f32_16x16x32_bf16 v[74:77], v[142:145], v[198:201], v[74:77]
	v_mfma_f32_16x16x32_bf16 v[58:61], v[134:137], v[214:217], v[58:61]
	v_mfma_f32_16x16x32_bf16 v[50:53], v[142:145], v[214:217], v[50:53]
	v_mfma_f32_16x16x32_bf16 v[30:33], v[146:149], v[162:165], v[30:33]
	v_mfma_f32_16x16x32_bf16 v[26:29], v[154:157], v[162:165], v[26:29]
	v_mfma_f32_16x16x32_bf16 v[22:25], v[146:149], v[186:189], v[22:25]
	v_mfma_f32_16x16x32_bf16 v[18:21], v[154:157], v[186:189], v[18:21]
	v_mfma_f32_16x16x32_bf16 v[14:17], v[146:149], v[194:197], v[14:17]
	v_mfma_f32_16x16x32_bf16 v[10:13], v[154:157], v[194:197], v[10:13]
	v_mfma_f32_16x16x32_bf16 v[6:9], v[146:149], v[202:205], v[6:9]
	v_mfma_f32_16x16x32_bf16 v[2:5], v[154:157], v[202:205], v[2:5]
	v_mfma_f32_16x16x32_bf16 v[30:33], v[150:153], v[166:169], v[30:33]
	v_mfma_f32_16x16x32_bf16 v[26:29], v[158:161], v[166:169], v[26:29]
	v_mfma_f32_16x16x32_bf16 v[22:25], v[150:153], v[190:193], v[22:25]
	v_mfma_f32_16x16x32_bf16 v[18:21], v[158:161], v[190:193], v[18:21]
	v_mfma_f32_16x16x32_bf16 v[14:17], v[150:153], v[198:201], v[14:17]
	v_mfma_f32_16x16x32_bf16 v[10:13], v[158:161], v[198:201], v[10:13]
	v_mfma_f32_16x16x32_bf16 v[6:9], v[150:153], v[214:217], v[6:9]
	v_mfma_f32_16x16x32_bf16 v[2:5], v[158:161], v[214:217], v[2:5]
	s_barrier
	s_add_i32 s78, 0, 0x18000
	s_add_i32 s79, 0, 0x1c000
	v_add_u32_e32 v142, s78, v208
	v_add_u32_e32 v158, s79, v208
	ds_read_b128 v[130:133], v142
	ds_read_b128 v[134:137], v142 offset:1024
	ds_read_b128 v[138:141], v142 offset:2048
	ds_read_b128 v[142:145], v142 offset:3072
	ds_read_b128 v[146:149], v158
	ds_read_b128 v[150:153], v158 offset:1024
	ds_read_b128 v[154:157], v158 offset:2048
	ds_read_b128 v[158:161], v158 offset:3072
	s_add_u32 s42, s42, 0xb0000
	s_addc_u32 s43, s43, 0
	s_mov_b32 m0, s52
	v_lshl_add_u64 v[226:227], s[42:43], 0, v[170:171]
	ds_read_b128 v[162:165], v212 offset:32768
	ds_read_b128 v[166:169], v212 offset:33792
	ds_read_b128 v[186:189], v212 offset:34816
	ds_read_b128 v[190:193], v212 offset:35840
	ds_read_b128 v[194:197], v212 offset:36864
	ds_read_b128 v[198:201], v212 offset:37888
	ds_read_b128 v[202:205], v212 offset:38912
	ds_read_b128 v[214:217], v212 offset:39936
	global_load_lds_dwordx4 v[226:227], off
	v_lshl_add_u64 v[226:227], s[42:43], 0, v[174:175]
	s_mov_b32 m0, s53
	s_nop 0
	global_load_lds_dwordx4 v[226:227], off
	s_waitcnt vmcnt(8)
	s_waitcnt lgkmcnt(0)
	s_barrier
	s_waitcnt lgkmcnt(0)
	v_mfma_f32_16x16x32_bf16 v[126:129], v[130:133], v[162:165], v[126:129]
	v_mfma_f32_16x16x32_bf16 v[122:125], v[138:141], v[162:165], v[122:125]
	v_mfma_f32_16x16x32_bf16 v[118:121], v[130:133], v[186:189], v[118:121]
	v_mfma_f32_16x16x32_bf16 v[114:117], v[138:141], v[186:189], v[114:117]
	v_mfma_f32_16x16x32_bf16 v[110:113], v[130:133], v[194:197], v[110:113]
	v_mfma_f32_16x16x32_bf16 v[106:109], v[138:141], v[194:197], v[106:109]
	v_mfma_f32_16x16x32_bf16 v[102:105], v[130:133], v[202:205], v[102:105]
	v_mfma_f32_16x16x32_bf16 v[98:101], v[138:141], v[202:205], v[98:101]
	v_mfma_f32_16x16x32_bf16 v[126:129], v[134:137], v[166:169], v[126:129]
	v_mfma_f32_16x16x32_bf16 v[122:125], v[142:145], v[166:169], v[122:125]
	v_mfma_f32_16x16x32_bf16 v[118:121], v[134:137], v[190:193], v[118:121]
	v_mfma_f32_16x16x32_bf16 v[114:117], v[142:145], v[190:193], v[114:117]
	v_mfma_f32_16x16x32_bf16 v[110:113], v[134:137], v[198:201], v[110:113]
	v_mfma_f32_16x16x32_bf16 v[106:109], v[142:145], v[198:201], v[106:109]
	v_mfma_f32_16x16x32_bf16 v[102:105], v[134:137], v[214:217], v[102:105]
	v_mfma_f32_16x16x32_bf16 v[98:101], v[142:145], v[214:217], v[98:101]
	v_mfma_f32_16x16x32_bf16 v[70:73], v[146:149], v[162:165], v[70:73]
	v_mfma_f32_16x16x32_bf16 v[66:69], v[154:157], v[162:165], v[66:69]
	v_mfma_f32_16x16x32_bf16 v[62:65], v[146:149], v[186:189], v[62:65]
	v_mfma_f32_16x16x32_bf16 v[54:57], v[154:157], v[186:189], v[54:57]
	v_mfma_f32_16x16x32_bf16 v[46:49], v[146:149], v[194:197], v[46:49]
	v_mfma_f32_16x16x32_bf16 v[42:45], v[154:157], v[194:197], v[42:45]
	v_mfma_f32_16x16x32_bf16 v[38:41], v[146:149], v[202:205], v[38:41]
	v_mfma_f32_16x16x32_bf16 v[34:37], v[154:157], v[202:205], v[34:37]
	v_mfma_f32_16x16x32_bf16 v[70:73], v[150:153], v[166:169], v[70:73]
	v_mfma_f32_16x16x32_bf16 v[66:69], v[158:161], v[166:169], v[66:69]
	v_mfma_f32_16x16x32_bf16 v[62:65], v[150:153], v[190:193], v[62:65]
	v_mfma_f32_16x16x32_bf16 v[54:57], v[158:161], v[190:193], v[54:57]
	v_mfma_f32_16x16x32_bf16 v[46:49], v[150:153], v[198:201], v[46:49]
	v_mfma_f32_16x16x32_bf16 v[42:45], v[158:161], v[198:201], v[42:45]
	v_mfma_f32_16x16x32_bf16 v[38:41], v[150:153], v[214:217], v[38:41]
	v_mfma_f32_16x16x32_bf16 v[34:37], v[158:161], v[214:217], v[34:37]
	s_barrier
	s_add_i32 s42, s78, s48
	v_lshl_add_u64 v[218:219], v[218:219], 0, s[14:15]
	s_mov_b32 m0, s42
	ds_read_b128 v[162:165], v212 offset:49152
	ds_read_b128 v[166:169], v212 offset:50176
	ds_read_b128 v[186:189], v212 offset:51200
	ds_read_b128 v[190:193], v212 offset:52224
	ds_read_b128 v[194:197], v212 offset:53248
	ds_read_b128 v[198:201], v212 offset:54272
	ds_read_b128 v[202:205], v212 offset:55296
	ds_read_b128 v[214:217], v212 offset:56320
	global_load_lds_dwordx4 v[218:219], off
	s_add_i32 m0, s42, 0x2000
	s_add_u32 s40, s40, 0xb0080
	v_lshl_add_u64 v[218:219], v[220:221], 0, s[14:15]
	s_addc_u32 s41, s41, 0
	s_add_i32 s42, s79, s48
	global_load_lds_dwordx4 v[218:219], off
	v_lshl_add_u64 v[218:219], s[40:41], 0, v[172:173]
	s_mov_b32 m0, s42
	s_nop 0
	global_load_lds_dwordx4 v[218:219], off
	v_lshl_add_u64 v[218:219], s[40:41], 0, v[176:177]
	s_add_i32 m0, s42, 0x2000
	s_nop 0
	global_load_lds_dwordx4 v[218:219], off
	v_lshl_add_u64 v[218:219], v[222:223], 0, s[14:15]
	s_mov_b32 m0, s58
	s_nop 0
	global_load_lds_dwordx4 v[218:219], off
	v_lshl_add_u64 v[218:219], v[224:225], 0, s[14:15]
	s_mov_b32 m0, s59
	s_nop 0
	global_load_lds_dwordx4 v[218:219], off
	s_waitcnt vmcnt(8)
	s_waitcnt lgkmcnt(0)
	s_barrier
	s_waitcnt lgkmcnt(0)
	v_mfma_f32_16x16x32_bf16 v[94:97], v[130:133], v[162:165], v[94:97]
	v_mfma_f32_16x16x32_bf16 v[90:93], v[138:141], v[162:165], v[90:93]
	v_mfma_f32_16x16x32_bf16 v[86:89], v[130:133], v[186:189], v[86:89]
	v_mfma_f32_16x16x32_bf16 v[82:85], v[138:141], v[186:189], v[82:85]
	v_mfma_f32_16x16x32_bf16 v[78:81], v[130:133], v[194:197], v[78:81]
	v_mfma_f32_16x16x32_bf16 v[74:77], v[138:141], v[194:197], v[74:77]
	v_mfma_f32_16x16x32_bf16 v[58:61], v[130:133], v[202:205], v[58:61]
	v_mfma_f32_16x16x32_bf16 v[50:53], v[138:141], v[202:205], v[50:53]
	v_mfma_f32_16x16x32_bf16 v[94:97], v[134:137], v[166:169], v[94:97]
	v_mfma_f32_16x16x32_bf16 v[90:93], v[142:145], v[166:169], v[90:93]
	v_mfma_f32_16x16x32_bf16 v[86:89], v[134:137], v[190:193], v[86:89]
	v_mfma_f32_16x16x32_bf16 v[82:85], v[142:145], v[190:193], v[82:85]
	v_mfma_f32_16x16x32_bf16 v[78:81], v[134:137], v[198:201], v[78:81]
	v_mfma_f32_16x16x32_bf16 v[74:77], v[142:145], v[198:201], v[74:77]
	v_mfma_f32_16x16x32_bf16 v[58:61], v[134:137], v[214:217], v[58:61]
	v_mfma_f32_16x16x32_bf16 v[50:53], v[142:145], v[214:217], v[50:53]
	v_mfma_f32_16x16x32_bf16 v[30:33], v[146:149], v[162:165], v[30:33]
	v_mfma_f32_16x16x32_bf16 v[26:29], v[154:157], v[162:165], v[26:29]
	v_mfma_f32_16x16x32_bf16 v[22:25], v[146:149], v[186:189], v[22:25]
	v_mfma_f32_16x16x32_bf16 v[18:21], v[154:157], v[186:189], v[18:21]
	v_mfma_f32_16x16x32_bf16 v[14:17], v[146:149], v[194:197], v[14:17]
	v_mfma_f32_16x16x32_bf16 v[10:13], v[154:157], v[194:197], v[10:13]
	v_mfma_f32_16x16x32_bf16 v[6:9], v[146:149], v[202:205], v[6:9]
	v_mfma_f32_16x16x32_bf16 v[2:5], v[154:157], v[202:205], v[2:5]
	v_mfma_f32_16x16x32_bf16 v[30:33], v[150:153], v[166:169], v[30:33]
	v_mfma_f32_16x16x32_bf16 v[26:29], v[158:161], v[166:169], v[26:29]
	v_mfma_f32_16x16x32_bf16 v[22:25], v[150:153], v[190:193], v[22:25]
	v_mfma_f32_16x16x32_bf16 v[18:21], v[158:161], v[190:193], v[18:21]
	v_mfma_f32_16x16x32_bf16 v[14:17], v[150:153], v[198:201], v[14:17]
	v_mfma_f32_16x16x32_bf16 v[10:13], v[158:161], v[198:201], v[10:13]
	v_mfma_f32_16x16x32_bf16 v[6:9], v[150:153], v[214:217], v[6:9]
	v_mfma_f32_16x16x32_bf16 v[2:5], v[158:161], v[214:217], v[2:5]
	s_barrier
	s_add_i32 s77, s77, 2
	s_add_u32 s38, s38, 0x100
	s_addc_u32 s39, s39, 0
	s_add_u32 s44, s44, 0x100
	s_addc_u32 s45, s45, 0
	s_cmp_gt_u32 s77, 41
	s_cbranch_scc0 .LBB0_1541
	s_and_b64 vcc, exec, s[16:17]
	s_cbranch_vccz .LBB0_1544
	s_barrier
